# GEMM main loops: the last iteration skips the eight clamped duplicate loads of its second K step (waits count down 15..8)
# speedup vs baseline: 1.0048x; 1.0048x over previous
.LBB0_133:
	ds_read_b128 v[178:181], v130
	ds_read_b128 v[182:185], v130 offset:32
	ds_read_b128 v[186:189], v130 offset:4608
	ds_read_b128 v[190:193], v130 offset:4640
	ds_read_b128 v[194:197], v131 offset:36864
	ds_read_b128 v[198:201], v131 offset:36896
	ds_read_b128 v[202:205], v131 offset:41472
	ds_read_b128 v[206:209], v131 offset:41504
	s_waitcnt vmcnt(15)
	ds_write_b128 v139, v[94:97] offset:18432
	buffer_load_dwordx4 v[94:97], v140, s[40:43], s0 offen
	s_waitcnt lgkmcnt(4)
	v_mfma_f32_32x32x16_bf16 v[50:65], v[178:181], v[194:197], v[50:65]
	s_add_u32 s24, s44, s0
	s_addc_u32 s25, vcc_lo, s1
	s_and_b32 s25, s25, 0xffff
	s_waitcnt lgkmcnt(2)
	v_mfma_f32_32x32x16_bf16 v[34:49], v[178:181], v[202:205], v[34:49]
	s_waitcnt vmcnt(15)
	ds_write_b128 v139, v[90:93] offset:55296
	buffer_load_dwordx4 v[90:93], v140, s[24:27], 0 offen
	v_mfma_f32_32x32x16_bf16 v[18:33], v[186:189], v[194:197], v[18:33]
	v_mfma_f32_32x32x16_bf16 v[2:17], v[186:189], v[202:205], v[2:17]
	s_add_i32 s34, s0, 0x11000
	ds_read_b128 v[178:181], v130 offset:64
	ds_read_b128 v[186:189], v130 offset:4672
	ds_read_b128 v[194:197], v131 offset:36928
	ds_read_b128 v[202:205], v131 offset:41536
	s_waitcnt vmcnt(15)
	ds_write_b128 v139, v[86:89] offset:23040
	buffer_load_dwordx4 v[86:89], v140, s[40:43], s34 offen
	v_mfma_f32_32x32x16_bf16 v[50:65], v[182:185], v[198:201], v[50:65]
	s_waitcnt lgkmcnt(7)
	v_mfma_f32_32x32x16_bf16 v[34:49], v[182:185], v[206:209], v[34:49]
	s_waitcnt vmcnt(15)
	ds_write_b128 v139, v[82:85] offset:59904
	buffer_load_dwordx4 v[82:85], v140, s[24:27], s33 offen
	v_mfma_f32_32x32x16_bf16 v[18:33], v[190:193], v[198:201], v[18:33]
	v_mfma_f32_32x32x16_bf16 v[2:17], v[190:193], v[206:209], v[2:17]
	s_add_i32 s34, s0, 0x22000
	ds_read_b128 v[182:185], v130 offset:96
	ds_read_b128 v[190:193], v130 offset:4704
	ds_read_b128 v[198:201], v131 offset:36960
	ds_read_b128 v[206:209], v131 offset:41568
	s_waitcnt vmcnt(15)
	ds_write_b128 v139, v[78:81] offset:27648
	buffer_load_dwordx4 v[78:81], v140, s[40:43], s34 offen
	s_waitcnt lgkmcnt(8)
	v_mfma_f32_32x32x16_bf16 v[50:65], v[178:181], v[194:197], v[50:65]
	s_waitcnt lgkmcnt(7)
	v_mfma_f32_32x32x16_bf16 v[34:49], v[178:181], v[202:205], v[34:49]
	s_waitcnt vmcnt(15)
	ds_write_b128 v139, v[74:77] offset:64512
	buffer_load_dwordx4 v[74:77], v140, s[24:27], s29 offen
	v_mfma_f32_32x32x16_bf16 v[18:33], v[186:189], v[194:197], v[18:33]
	v_mfma_f32_32x32x16_bf16 v[2:17], v[186:189], v[202:205], v[2:17]
	s_add_i32 s34, s0, 0x33000
	s_waitcnt vmcnt(15)
	ds_write_b128 v139, v[70:73] offset:32256
	buffer_load_dwordx4 v[70:73], v140, s[40:43], s34 offen
	s_waitcnt lgkmcnt(4)
	v_mfma_f32_32x32x16_bf16 v[50:65], v[182:185], v[198:201], v[50:65]
	s_waitcnt lgkmcnt(3)
	v_mfma_f32_32x32x16_bf16 v[34:49], v[182:185], v[206:209], v[34:49]
	s_waitcnt vmcnt(15)
	ds_write_b128 v142, v[66:69] offset:13824
	buffer_load_dwordx4 v[66:69], v140, s[24:27], s3 offen
	v_mfma_f32_32x32x16_bf16 v[18:33], v[190:193], v[198:201], v[18:33]
	v_mfma_f32_32x32x16_bf16 v[2:17], v[190:193], v[206:209], v[2:17]
	s_min_u32 s24, vcc_hi, 11
	s_lshl_b32 s34, s24, 7
	s_add_i32 s24, s34, 0x200
	s_waitcnt lgkmcnt(0)
	s_barrier
	s_cmp_eq_u32 vcc_hi, 12
	s_cbranch_scc1 .Llast_133
	ds_read_b128 v[178:181], v130 offset:18432
	ds_read_b128 v[182:185], v130 offset:18464
	ds_read_b128 v[186:189], v130 offset:23040
	ds_read_b128 v[190:193], v130 offset:23072
	ds_read_b128 v[194:197], v131 offset:55296
	ds_read_b128 v[198:201], v131 offset:55328
	ds_read_b128 v[202:205], v131 offset:59904
	ds_read_b128 v[206:209], v131 offset:59936
	s_waitcnt vmcnt(15)
	ds_write_b128 v139, v[102:105]
	buffer_load_dwordx4 v[102:105], v140, s[40:43], s24 offen
	s_waitcnt lgkmcnt(4)
	v_mfma_f32_32x32x16_bf16 v[50:65], v[178:181], v[194:197], v[50:65]
	s_add_u32 s24, s44, s24
	s_addc_u32 s25, vcc_lo, 0
	s_and_b32 s25, s25, 0xffff
	s_waitcnt lgkmcnt(2)
	v_mfma_f32_32x32x16_bf16 v[34:49], v[178:181], v[202:205], v[34:49]
	s_waitcnt vmcnt(15)
	ds_write_b128 v139, v[98:101] offset:36864
	buffer_load_dwordx4 v[98:101], v140, s[24:27], 0 offen
	v_mfma_f32_32x32x16_bf16 v[18:33], v[186:189], v[194:197], v[18:33]
	v_mfma_f32_32x32x16_bf16 v[2:17], v[186:189], v[202:205], v[2:17]
	s_add_i32 s35, s34, 0x11200
	ds_read_b128 v[178:181], v130 offset:18496
	ds_read_b128 v[186:189], v130 offset:23104
	ds_read_b128 v[194:197], v131 offset:55360
	ds_read_b128 v[202:205], v131 offset:59968
	s_waitcnt vmcnt(15)
	ds_write_b128 v139, v[106:109] offset:4608
	buffer_load_dwordx4 v[106:109], v140, s[40:43], s35 offen
	v_mfma_f32_32x32x16_bf16 v[50:65], v[182:185], v[198:201], v[50:65]
	s_waitcnt lgkmcnt(7)
	v_mfma_f32_32x32x16_bf16 v[34:49], v[182:185], v[206:209], v[34:49]
	s_waitcnt vmcnt(15)
	ds_write_b128 v139, v[110:113] offset:41472
	buffer_load_dwordx4 v[110:113], v140, s[24:27], s33 offen
	v_mfma_f32_32x32x16_bf16 v[18:33], v[190:193], v[198:201], v[18:33]
	v_mfma_f32_32x32x16_bf16 v[2:17], v[190:193], v[206:209], v[2:17]
	s_add_i32 s35, s34, 0x22200
	ds_read_b128 v[182:185], v130 offset:18528
	ds_read_b128 v[190:193], v130 offset:23136
	ds_read_b128 v[198:201], v131 offset:55392
	ds_read_b128 v[206:209], v131 offset:60000
	s_waitcnt vmcnt(15)
	ds_write_b128 v139, v[114:117] offset:9216
	buffer_load_dwordx4 v[114:117], v140, s[40:43], s35 offen
	s_waitcnt lgkmcnt(8)
	v_mfma_f32_32x32x16_bf16 v[50:65], v[178:181], v[194:197], v[50:65]
	s_waitcnt lgkmcnt(7)
	v_mfma_f32_32x32x16_bf16 v[34:49], v[178:181], v[202:205], v[34:49]
	s_waitcnt vmcnt(15)
	ds_write_b128 v139, v[118:121] offset:46080
	buffer_load_dwordx4 v[118:121], v140, s[24:27], s29 offen
	v_mfma_f32_32x32x16_bf16 v[18:33], v[186:189], v[194:197], v[18:33]
	v_mfma_f32_32x32x16_bf16 v[2:17], v[186:189], v[202:205], v[2:17]
	s_add_i32 s34, s34, 0x33200
	s_waitcnt vmcnt(15)
	ds_write_b128 v139, v[122:125] offset:13824
	buffer_load_dwordx4 v[122:125], v140, s[40:43], s34 offen
	s_waitcnt lgkmcnt(4)
	v_mfma_f32_32x32x16_bf16 v[50:65], v[182:185], v[198:201], v[50:65]
	s_waitcnt lgkmcnt(3)
	v_mfma_f32_32x32x16_bf16 v[34:49], v[182:185], v[206:209], v[34:49]
	s_waitcnt vmcnt(15)
	ds_write_b128 v139, v[126:129] offset:50688
	buffer_load_dwordx4 v[126:129], v140, s[24:27], s3 offen
	v_mfma_f32_32x32x16_bf16 v[18:33], v[190:193], v[198:201], v[18:33]
	v_mfma_f32_32x32x16_bf16 v[2:17], v[190:193], v[206:209], v[2:17]
	s_add_i32 vcc_hi, vcc_hi, 2
	s_add_u32 s0, s0, 0x100
	s_addc_u32 s1, s1, 0
	s_cmp_lt_u32 vcc_hi, 14
	s_waitcnt lgkmcnt(0)
	s_barrier
	s_cbranch_scc1 .LBB0_133
	s_branch .Ltail_133
.Llast_133:
	ds_read_b128 v[178:181], v130 offset:18432
	ds_read_b128 v[182:185], v130 offset:18464
	ds_read_b128 v[186:189], v130 offset:23040
	ds_read_b128 v[190:193], v130 offset:23072
	ds_read_b128 v[194:197], v131 offset:55296
	ds_read_b128 v[198:201], v131 offset:55328
	ds_read_b128 v[202:205], v131 offset:59904
	ds_read_b128 v[206:209], v131 offset:59936
	s_waitcnt vmcnt(15)
	ds_write_b128 v139, v[102:105]
	s_waitcnt lgkmcnt(4)
	v_mfma_f32_32x32x16_bf16 v[50:65], v[178:181], v[194:197], v[50:65]
	s_add_u32 s24, s44, s24
	s_addc_u32 s25, vcc_lo, 0
	s_and_b32 s25, s25, 0xffff
	s_waitcnt lgkmcnt(2)
	v_mfma_f32_32x32x16_bf16 v[34:49], v[178:181], v[202:205], v[34:49]
	s_waitcnt vmcnt(14)
	ds_write_b128 v139, v[98:101] offset:36864
	v_mfma_f32_32x32x16_bf16 v[18:33], v[186:189], v[194:197], v[18:33]
	v_mfma_f32_32x32x16_bf16 v[2:17], v[186:189], v[202:205], v[2:17]
	s_add_i32 s35, s34, 0x11200
	ds_read_b128 v[178:181], v130 offset:18496
	ds_read_b128 v[186:189], v130 offset:23104
	ds_read_b128 v[194:197], v131 offset:55360
	ds_read_b128 v[202:205], v131 offset:59968
	s_waitcnt vmcnt(13)
	ds_write_b128 v139, v[106:109] offset:4608
	v_mfma_f32_32x32x16_bf16 v[50:65], v[182:185], v[198:201], v[50:65]
	s_waitcnt lgkmcnt(7)
	v_mfma_f32_32x32x16_bf16 v[34:49], v[182:185], v[206:209], v[34:49]
	s_waitcnt vmcnt(12)
	ds_write_b128 v139, v[110:113] offset:41472
	v_mfma_f32_32x32x16_bf16 v[18:33], v[190:193], v[198:201], v[18:33]
	v_mfma_f32_32x32x16_bf16 v[2:17], v[190:193], v[206:209], v[2:17]
	s_add_i32 s35, s34, 0x22200
	ds_read_b128 v[182:185], v130 offset:18528
	ds_read_b128 v[190:193], v130 offset:23136
	ds_read_b128 v[198:201], v131 offset:55392
	ds_read_b128 v[206:209], v131 offset:60000
	s_waitcnt vmcnt(11)
	ds_write_b128 v139, v[114:117] offset:9216
	s_waitcnt lgkmcnt(8)
	v_mfma_f32_32x32x16_bf16 v[50:65], v[178:181], v[194:197], v[50:65]
	s_waitcnt lgkmcnt(7)
	v_mfma_f32_32x32x16_bf16 v[34:49], v[178:181], v[202:205], v[34:49]
	s_waitcnt vmcnt(10)
	ds_write_b128 v139, v[118:121] offset:46080
	v_mfma_f32_32x32x16_bf16 v[18:33], v[186:189], v[194:197], v[18:33]
	v_mfma_f32_32x32x16_bf16 v[2:17], v[186:189], v[202:205], v[2:17]
	s_add_i32 s34, s34, 0x33200
	s_waitcnt vmcnt(9)
	ds_write_b128 v139, v[122:125] offset:13824
	s_waitcnt lgkmcnt(4)
	v_mfma_f32_32x32x16_bf16 v[50:65], v[182:185], v[198:201], v[50:65]
	s_waitcnt lgkmcnt(3)
	v_mfma_f32_32x32x16_bf16 v[34:49], v[182:185], v[206:209], v[34:49]
	s_waitcnt vmcnt(8)
	ds_write_b128 v139, v[126:129] offset:50688
	v_mfma_f32_32x32x16_bf16 v[18:33], v[190:193], v[198:201], v[18:33]
	v_mfma_f32_32x32x16_bf16 v[2:17], v[190:193], v[206:209], v[2:17]
	s_add_i32 vcc_hi, vcc_hi, 2
	s_add_u32 s0, s0, 0x100
	s_addc_u32 s1, s1, 0
	s_cmp_lt_u32 vcc_hi, 14
	s_waitcnt lgkmcnt(0)
	s_barrier
	s_branch .Ltail_133
.Ltail_133:
	s_waitcnt vmcnt(6)
	ds_read_b128 v[98:101], v130
	ds_read_b128 v[102:105], v131 offset:36864
	s_waitcnt vmcnt(5)
	ds_read_b128 v[106:109], v130 offset:32
	s_waitcnt vmcnt(4)
	ds_read_b128 v[110:113], v131 offset:36896
	s_waitcnt vmcnt(3)
	ds_read_b128 v[114:117], v131 offset:41472
	s_waitcnt vmcnt(2)
	ds_read_b128 v[118:121], v130 offset:4608
	s_waitcnt vmcnt(1)
	ds_read_b128 v[122:125], v130 offset:4640
	s_waitcnt vmcnt(0)
	ds_read_b128 v[126:129], v131 offset:41504
	s_waitcnt lgkmcnt(3)
	v_mfma_f32_32x32x16_bf16 v[34:49], v[98:101], v[114:117], v[34:49]
	ds_write_b128 v139, v[94:97] offset:18432
	v_mfma_f32_32x32x16_bf16 v[50:65], v[98:101], v[102:105], v[50:65]
	s_waitcnt lgkmcnt(3)
	v_mfma_f32_32x32x16_bf16 v[18:33], v[118:121], v[102:105], v[18:33]
	ds_write_b128 v139, v[90:93] offset:55296
	v_mfma_f32_32x32x16_bf16 v[2:17], v[118:121], v[114:117], v[2:17]
	v_mfma_f32_32x32x16_bf16 v[50:65], v[106:109], v[110:113], v[50:65]
	ds_read_b128 v[90:93], v130 offset:64
	ds_read_b128 v[94:97], v130 offset:4672
	ds_read_b128 v[98:101], v131 offset:36928
	ds_read_b128 v[102:105], v131 offset:41536
	ds_write_b128 v139, v[86:89] offset:23040
	s_waitcnt lgkmcnt(7)
	v_mfma_f32_32x32x16_bf16 v[34:49], v[106:109], v[126:129], v[34:49]
	v_mfma_f32_32x32x16_bf16 v[18:33], v[122:125], v[110:113], v[18:33]
	ds_write_b128 v139, v[82:85] offset:59904
	v_mfma_f32_32x32x16_bf16 v[2:17], v[122:125], v[126:129], v[2:17]
	s_waitcnt lgkmcnt(3)
	v_mfma_f32_32x32x16_bf16 v[50:65], v[90:93], v[98:101], v[50:65]
	ds_read_b128 v[82:85], v130 offset:96
	ds_read_b128 v[86:89], v130 offset:4704
	ds_read_b128 v[106:109], v131 offset:36960
	ds_read_b128 v[110:113], v131 offset:41568
	ds_write_b128 v139, v[78:81] offset:27648
	s_waitcnt lgkmcnt(7)
	v_mfma_f32_32x32x16_bf16 v[34:49], v[90:93], v[102:105], v[34:49]
	v_mfma_f32_32x32x16_bf16 v[18:33], v[94:97], v[98:101], v[18:33]
	ds_write_b128 v139, v[74:77] offset:64512
	v_mfma_f32_32x32x16_bf16 v[2:17], v[94:97], v[102:105], v[2:17]
	s_waitcnt lgkmcnt(3)
	v_mfma_f32_32x32x16_bf16 v[50:65], v[82:85], v[106:109], v[50:65]
	ds_write_b128 v139, v[70:73] offset:32256
	s_waitcnt lgkmcnt(3)
	v_mfma_f32_32x32x16_bf16 v[34:49], v[82:85], v[110:113], v[34:49]
	v_mfma_f32_32x32x16_bf16 v[18:33], v[86:89], v[106:109], v[18:33]
	ds_write_b128 v142, v[66:69] offset:13824
	v_mfma_f32_32x32x16_bf16 v[2:17], v[86:89], v[110:113], v[2:17]
	s_waitcnt lgkmcnt(0)
	s_barrier
	ds_read_b128 v[66:69], v130 offset:18432
	ds_read_b128 v[70:73], v131 offset:55296
	ds_read_b128 v[74:77], v130 offset:18464
	ds_read_b128 v[78:81], v131 offset:55328
	ds_read_b128 v[82:85], v131 offset:59904
	ds_read_b128 v[86:89], v130 offset:23040
	ds_read_b128 v[90:93], v130 offset:23072
	ds_read_b128 v[94:97], v131 offset:59936
	s_waitcnt lgkmcnt(6)
	v_mfma_f32_32x32x16_bf16 v[50:65], v[66:69], v[70:73], v[50:65]
	s_waitcnt lgkmcnt(3)
	v_mfma_f32_32x32x16_bf16 v[34:49], v[66:69], v[82:85], v[34:49]
	s_waitcnt lgkmcnt(2)
	v_mfma_f32_32x32x16_bf16 v[18:33], v[86:89], v[70:73], v[18:33]
	v_mfma_f32_32x32x16_bf16 v[2:17], v[86:89], v[82:85], v[2:17]
	v_mfma_f32_32x32x16_bf16 v[50:65], v[74:77], v[78:81], v[50:65]
	ds_read_b128 v[66:69], v130 offset:18496
	ds_read_b128 v[70:73], v130 offset:23104
	ds_read_b128 v[82:85], v131 offset:55360
	ds_read_b128 v[86:89], v131 offset:59968
	s_waitcnt lgkmcnt(4)
	v_mfma_f32_32x32x16_bf16 v[34:49], v[74:77], v[94:97], v[34:49]
	v_mfma_f32_32x32x16_bf16 v[18:33], v[90:93], v[78:81], v[18:33]
	v_mfma_f32_32x32x16_bf16 v[2:17], v[90:93], v[94:97], v[2:17]
	s_waitcnt lgkmcnt(1)
	v_mfma_f32_32x32x16_bf16 v[50:65], v[66:69], v[82:85], v[50:65]
	ds_read_b128 v[74:77], v130 offset:18528
	ds_read_b128 v[78:81], v130 offset:23136
	ds_read_b128 v[90:93], v131 offset:55392
	ds_read_b128 v[94:97], v131 offset:60000
	s_waitcnt lgkmcnt(4)
	v_mfma_f32_32x32x16_bf16 v[34:49], v[66:69], v[86:89], v[34:49]
	v_mfma_f32_32x32x16_bf16 v[18:33], v[70:73], v[82:85], v[18:33]
	v_mfma_f32_32x32x16_bf16 v[2:17], v[70:73], v[86:89], v[2:17]
	s_waitcnt lgkmcnt(1)
	v_mfma_f32_32x32x16_bf16 v[50:65], v[74:77], v[90:93], v[50:65]
	s_waitcnt lgkmcnt(0)
	v_mfma_f32_32x32x16_bf16 v[34:49], v[74:77], v[94:97], v[34:49]
	v_mfma_f32_32x32x16_bf16 v[18:33], v[78:81], v[90:93], v[18:33]
	v_mfma_f32_32x32x16_bf16 v[2:17], v[78:81], v[94:97], v[2:17]
	v_lshrrev_b32_e32 v227, 5, v136
	s_lshl_b32 s0, s51, 9
	v_lshl_add_u32 v223, v227, 12, v222
	v_add_u32_e32 v223, s0, v223
	v_mov_b32_e32 v228, v223
	global_load_dwordx4 v[98:101], v228, s[68:69]
	v_add_u32_e32 v228, 0x8000, v228
	global_load_dwordx4 v[102:105], v228, s[68:69]
	v_add_u32_e32 v228, 0x8000, v228
	global_load_dwordx4 v[106:109], v228, s[68:69]
	v_add_u32_e32 v228, 0x8000, v228
	global_load_dwordx4 v[110:113], v228, s[68:69]
	v_add_u32_e32 v228, 0x8000, v228
	global_load_dwordx4 v[114:117], v228, s[68:69]
	v_add_u32_e32 v228, 0x8000, v228
	global_load_dwordx4 v[118:121], v228, s[68:69]
	v_add_u32_e32 v228, 0x8000, v228
	global_load_dwordx4 v[122:125], v228, s[68:69]
	v_add_u32_e32 v228, 0x8000, v228
	global_load_dwordx4 v[126:129], v228, s[68:69]
	v_add_u32_e32 v228, 0x8000, v228
	global_load_dwordx4 v[178:181], v228, s[68:69]
	v_add_u32_e32 v228, 0x8000, v228
	global_load_dwordx4 v[182:185], v228, s[68:69]
	v_add_u32_e32 v228, 0x8000, v228
	global_load_dwordx4 v[186:189], v228, s[68:69]
	v_add_u32_e32 v228, 0x8000, v228
	global_load_dwordx4 v[190:193], v228, s[68:69]
	v_add_u32_e32 v228, 0x8000, v228
	global_load_dwordx4 v[194:197], v228, s[68:69]
	v_add_u32_e32 v228, 0x8000, v228
	global_load_dwordx4 v[198:201], v228, s[68:69]
	v_add_u32_e32 v228, 0x8000, v228
	global_load_dwordx4 v[202:205], v228, s[68:69]
	v_add_u32_e32 v228, 0x8000, v228
	global_load_dwordx4 v[206:209], v228, s[68:69]
	v_lshl_or_b32 v66, v138, 2, v141
	s_movk_i32 s0, 0x210
	v_and_or_b32 v67, v136, 64, v137
	v_mul_lo_u32 v66, v66, s0
	v_lshl_add_u32 v66, v67, 2, v66
	s_barrier
	s_nop 3
	ds_write2_b32 v66, v50, v34 offset1:32
	ds_write2_b32 v66, v51, v35 offset0:132 offset1:164
	v_add_u32_e32 v34, 0x400, v66
	ds_write2_b32 v34, v52, v36 offset0:8 offset1:40
	ds_write2_b32 v34, v53, v37 offset0:140 offset1:172
	v_add_u32_e32 v34, 0x1000, v66
	ds_write2_b32 v34, v54, v38 offset0:32 offset1:64
	ds_write2_b32 v34, v55, v39 offset0:164 offset1:196
	v_add_u32_e32 v34, 0x1400, v66
	ds_write2_b32 v34, v56, v40 offset0:40 offset1:72
	ds_write2_b32 v34, v57, v41 offset0:172 offset1:204
	v_add_u32_e32 v34, 0x2000, v66
	ds_write2_b32 v34, v58, v42 offset0:64 offset1:96
	ds_write2_b32 v34, v59, v43 offset0:196 offset1:228
	v_add_u32_e32 v34, 0x2400, v66
	ds_write2_b32 v34, v60, v44 offset0:72 offset1:104
	ds_write2_b32 v34, v61, v45 offset0:204 offset1:236
	v_add_u32_e32 v34, 0x3000, v66
	ds_write2_b32 v34, v62, v46 offset0:96 offset1:128
	v_add_u32_e32 v34, 0x3200, v66
	ds_write2_b32 v34, v63, v47 offset0:100 offset1:132
	v_add_u32_e32 v34, 0x3400, v66
	ds_write2_b32 v34, v64, v48 offset0:104 offset1:136
	v_add_u32_e32 v34, 0x3600, v66
	ds_write2_b32 v34, v65, v49 offset0:108 offset1:140
	v_add_u32_e32 v34, 0x4000, v66
	ds_write2_b32 v34, v18, v2 offset0:128 offset1:160
	v_add_u32_e32 v2, 0x4400, v66
	ds_write2_b32 v2, v19, v3 offset0:4 offset1:36
	ds_write2_b32 v2, v20, v4 offset0:136 offset1:168
	v_add_u32_e32 v2, 0x4800, v66
	ds_write2_b32 v2, v21, v5 offset0:12 offset1:44
	v_add_u32_e32 v2, 0x5000, v66
	ds_write2_b32 v2, v22, v6 offset0:160 offset1:192
	v_add_u32_e32 v2, 0x5400, v66
	ds_write2_b32 v2, v23, v7 offset0:36 offset1:68
	ds_write2_b32 v2, v24, v8 offset0:168 offset1:200
	v_add_u32_e32 v2, 0x5800, v66
	ds_write2_b32 v2, v25, v9 offset0:44 offset1:76
	v_add_u32_e32 v2, 0x6000, v66
	ds_write2_b32 v2, v26, v10 offset0:192 offset1:224
	v_add_u32_e32 v2, 0x6400, v66
	ds_write2_b32 v2, v27, v11 offset0:68 offset1:100
	ds_write2_b32 v2, v28, v12 offset0:200 offset1:232
	v_add_u32_e32 v2, 0x6800, v66
	ds_write2_b32 v2, v29, v13 offset0:76 offset1:108
	v_add_u32_e32 v2, 0x7200, v66
	ds_write2_b32 v2, v30, v14 offset0:96 offset1:128
	v_add_u32_e32 v2, 0x7400, v66
	ds_write2_b32 v2, v31, v15 offset0:100 offset1:132
	v_add_u32_e32 v2, 0x7600, v66
	ds_write2_b32 v2, v32, v16 offset0:104 offset1:136
	v_add_u32_e32 v2, 0x7800, v66
	ds_write2_b32 v2, v33, v17 offset0:108 offset1:140
	s_waitcnt lgkmcnt(0)
	s_barrier
	v_lshrrev_b32_e32 v227, 5, v136
	v_mul_u32_u24_e32 v225, 0x210, v227
	v_add_u32_e32 v225, v225, v222
	ds_read_b128 v[2:5], v225
	ds_read_b128 v[6:9], v225 offset:4224
	ds_read_b128 v[10:13], v225 offset:8448
	ds_read_b128 v[14:17], v225 offset:12672
	ds_read_b128 v[18:21], v225 offset:16896
	ds_read_b128 v[22:25], v225 offset:21120
	ds_read_b128 v[26:29], v225 offset:25344
	ds_read_b128 v[30:33], v225 offset:29568
	ds_read_b128 v[34:37], v225 offset:33792
	ds_read_b128 v[38:41], v225 offset:38016
	ds_read_b128 v[42:45], v225 offset:42240
	ds_read_b128 v[46:49], v225 offset:46464
	ds_read_b128 v[50:53], v225 offset:50688
	ds_read_b128 v[54:57], v225 offset:54912
	ds_read_b128 v[58:61], v225 offset:59136
	ds_read_b128 v[62:65], v225 offset:63360
	v_mul_u32_u24_e32 v224, 0x880, v227
	s_lshl_b32 s0, s51, 8
	v_lshrrev_b32_e32 v228, 1, v222
	v_add3_u32 v224, v224, v228, s0
	v_lshlrev_b32_e32 v226, 2, v227
	s_waitcnt lgkmcnt(0)
	s_waitcnt vmcnt(15)
	v_pk_fma_f32 v[2:3], v[2:3], v[210:211], v[98:99]
	v_pk_fma_f32 v[4:5], v[4:5], v[212:213], v[100:101]
	s_waitcnt vmcnt(14)
	v_pk_fma_f32 v[6:7], v[6:7], v[210:211], v[102:103]
	v_pk_fma_f32 v[8:9], v[8:9], v[212:213], v[104:105]
	s_waitcnt vmcnt(13)
	v_pk_fma_f32 v[10:11], v[10:11], v[210:211], v[106:107]
	v_pk_fma_f32 v[12:13], v[12:13], v[212:213], v[108:109]
	s_waitcnt vmcnt(12)
	v_pk_fma_f32 v[14:15], v[14:15], v[210:211], v[110:111]
	v_pk_fma_f32 v[16:17], v[16:17], v[212:213], v[112:113]
	s_waitcnt vmcnt(11)
	v_pk_fma_f32 v[18:19], v[18:19], v[210:211], v[114:115]
	v_pk_fma_f32 v[20:21], v[20:21], v[212:213], v[116:117]
	s_waitcnt vmcnt(10)
	v_pk_fma_f32 v[22:23], v[22:23], v[210:211], v[118:119]
	v_pk_fma_f32 v[24:25], v[24:25], v[212:213], v[120:121]
	s_waitcnt vmcnt(9)
	v_pk_fma_f32 v[26:27], v[26:27], v[210:211], v[122:123]
	v_pk_fma_f32 v[28:29], v[28:29], v[212:213], v[124:125]
	s_waitcnt vmcnt(8)
	v_pk_fma_f32 v[30:31], v[30:31], v[210:211], v[126:127]
	v_pk_fma_f32 v[32:33], v[32:33], v[212:213], v[128:129]
	s_waitcnt vmcnt(7)
	v_pk_fma_f32 v[34:35], v[34:35], v[210:211], v[178:179]
	v_pk_fma_f32 v[36:37], v[36:37], v[212:213], v[180:181]
	s_waitcnt vmcnt(6)
	v_pk_fma_f32 v[38:39], v[38:39], v[210:211], v[182:183]
	v_pk_fma_f32 v[40:41], v[40:41], v[212:213], v[184:185]
	s_waitcnt vmcnt(5)
	v_pk_fma_f32 v[42:43], v[42:43], v[210:211], v[186:187]
	v_pk_fma_f32 v[44:45], v[44:45], v[212:213], v[188:189]
	s_waitcnt vmcnt(4)
	v_pk_fma_f32 v[46:47], v[46:47], v[210:211], v[190:191]
	v_pk_fma_f32 v[48:49], v[48:49], v[212:213], v[192:193]
	s_waitcnt vmcnt(3)
	v_pk_fma_f32 v[50:51], v[50:51], v[210:211], v[194:195]
	v_pk_fma_f32 v[52:53], v[52:53], v[212:213], v[196:197]
	s_waitcnt vmcnt(2)
	v_pk_fma_f32 v[54:55], v[54:55], v[210:211], v[198:199]
	v_pk_fma_f32 v[56:57], v[56:57], v[212:213], v[200:201]
	s_waitcnt vmcnt(1)
	v_pk_fma_f32 v[58:59], v[58:59], v[210:211], v[202:203]
	v_pk_fma_f32 v[60:61], v[60:61], v[212:213], v[204:205]
	s_waitcnt vmcnt(0)
	v_pk_fma_f32 v[62:63], v[62:63], v[210:211], v[206:207]
	v_pk_fma_f32 v[64:65], v[64:65], v[212:213], v[208:209]
	v_mov_b32_e32 v228, v223
	global_store_dwordx4 v228, v[2:5], s[70:71] sc0 sc1
	v_add_u32_e32 v228, 0x8000, v228
	global_store_dwordx4 v228, v[6:9], s[70:71] sc0 sc1
	v_add_u32_e32 v228, 0x8000, v228
	global_store_dwordx4 v228, v[10:13], s[70:71] sc0 sc1
	v_add_u32_e32 v228, 0x8000, v228
	global_store_dwordx4 v228, v[14:17], s[70:71] sc0 sc1
	v_add_u32_e32 v228, 0x8000, v228
	global_store_dwordx4 v228, v[18:21], s[70:71] sc0 sc1
	v_add_u32_e32 v228, 0x8000, v228
	global_store_dwordx4 v228, v[22:25], s[70:71] sc0 sc1
	v_add_u32_e32 v228, 0x8000, v228
	global_store_dwordx4 v228, v[26:29], s[70:71] sc0 sc1
	v_add_u32_e32 v228, 0x8000, v228
	global_store_dwordx4 v228, v[30:33], s[70:71] sc0 sc1
	v_add_u32_e32 v228, 0x8000, v228
	global_store_dwordx4 v228, v[34:37], s[70:71] sc0 sc1
	v_add_u32_e32 v228, 0x8000, v228
	global_store_dwordx4 v228, v[38:41], s[70:71] sc0 sc1
	v_add_u32_e32 v228, 0x8000, v228
	global_store_dwordx4 v228, v[42:45], s[70:71] sc0 sc1
	v_add_u32_e32 v228, 0x8000, v228
	global_store_dwordx4 v228, v[46:49], s[70:71] sc0 sc1
	v_add_u32_e32 v228, 0x8000, v228
	global_store_dwordx4 v228, v[50:53], s[70:71] sc0 sc1
	v_add_u32_e32 v228, 0x8000, v228
	global_store_dwordx4 v228, v[54:57], s[70:71] sc0 sc1
	v_add_u32_e32 v228, 0x8000, v228
	global_store_dwordx4 v228, v[58:61], s[70:71] sc0 sc1
	v_add_u32_e32 v228, 0x8000, v228
	global_store_dwordx4 v228, v[62:65], s[70:71] sc0 sc1
	s_cmp_lg_u64 s[54:55], 0
	s_cbranch_scc0 .LBB0_122
	v_pk_add_f32 v[218:219], v[218:219], 1.0 op_sel_hi:[1,0]
	v_pk_add_f32 v[220:221], v[220:221], 1.0 op_sel_hi:[1,0]
	v_pk_mul_f32 v[214:215], v[214:215], v[218:219]
	v_pk_mul_f32 v[216:217], v[216:217], v[220:221]
	v_pk_mul_f32 v[98:99], v[2:3], v[2:3]
	v_pk_mul_f32 v[100:101], v[4:5], v[4:5]
	v_pk_mul_f32 v[102:103], v[6:7], v[6:7]
	v_pk_mul_f32 v[104:105], v[8:9], v[8:9]
	v_pk_mul_f32 v[106:107], v[10:11], v[10:11]
	v_pk_mul_f32 v[108:109], v[12:13], v[12:13]
	v_pk_mul_f32 v[110:111], v[14:15], v[14:15]
	v_pk_mul_f32 v[112:113], v[16:17], v[16:17]
	v_pk_mul_f32 v[114:115], v[18:19], v[18:19]
	v_pk_mul_f32 v[116:117], v[20:21], v[20:21]
	v_pk_mul_f32 v[118:119], v[22:23], v[22:23]
	v_pk_mul_f32 v[120:121], v[24:25], v[24:25]
	v_pk_mul_f32 v[122:123], v[26:27], v[26:27]
	v_pk_mul_f32 v[124:125], v[28:29], v[28:29]
	v_pk_mul_f32 v[126:127], v[30:31], v[30:31]
	v_pk_mul_f32 v[128:129], v[32:33], v[32:33]
	v_pk_mul_f32 v[178:179], v[34:35], v[34:35]
	v_pk_mul_f32 v[180:181], v[36:37], v[36:37]
	v_pk_mul_f32 v[182:183], v[38:39], v[38:39]
	v_pk_mul_f32 v[184:185], v[40:41], v[40:41]
	v_pk_mul_f32 v[186:187], v[42:43], v[42:43]
	v_pk_mul_f32 v[188:189], v[44:45], v[44:45]
	v_pk_mul_f32 v[190:191], v[46:47], v[46:47]
	v_pk_mul_f32 v[192:193], v[48:49], v[48:49]
	v_pk_mul_f32 v[194:195], v[50:51], v[50:51]
	v_pk_mul_f32 v[196:197], v[52:53], v[52:53]
	v_pk_mul_f32 v[198:199], v[54:55], v[54:55]
	v_pk_mul_f32 v[200:201], v[56:57], v[56:57]
	v_pk_mul_f32 v[202:203], v[58:59], v[58:59]
	v_pk_mul_f32 v[204:205], v[60:61], v[60:61]
	v_pk_mul_f32 v[206:207], v[62:63], v[62:63]
	v_pk_mul_f32 v[208:209], v[64:65], v[64:65]
	v_add_f32_e32 v229, v98, v99
	v_add_f32_e32 v230, v102, v103
	v_add_f32_e32 v231, v106, v107
	v_add_f32_e32 v232, v110, v111
	v_add_f32_e32 v233, v114, v115
	v_add_f32_e32 v234, v118, v119
	v_add_f32_e32 v235, v122, v123
	v_add_f32_e32 v236, v126, v127
	v_add_f32_e32 v237, v178, v179
	v_add_f32_e32 v238, v182, v183
	v_add_f32_e32 v239, v186, v187
	v_add_f32_e32 v240, v190, v191
	v_add_f32_e32 v241, v194, v195
	v_add_f32_e32 v242, v198, v199
	v_add_f32_e32 v243, v202, v203
	v_add_f32_e32 v244, v206, v207
	v_add_f32_e32 v229, v229, v100
	v_add_f32_e32 v230, v230, v104
	v_add_f32_e32 v231, v231, v108
	v_add_f32_e32 v232, v232, v112
	v_add_f32_e32 v233, v233, v116
	v_add_f32_e32 v234, v234, v120
	v_add_f32_e32 v235, v235, v124
	v_add_f32_e32 v236, v236, v128
	v_add_f32_e32 v237, v237, v180
	v_add_f32_e32 v238, v238, v184
	v_add_f32_e32 v239, v239, v188
	v_add_f32_e32 v240, v240, v192
	v_add_f32_e32 v241, v241, v196
	v_add_f32_e32 v242, v242, v200
	v_add_f32_e32 v243, v243, v204
	v_add_f32_e32 v244, v244, v208
	v_add_f32_e32 v229, v229, v101
	v_add_f32_e32 v230, v230, v105
	v_add_f32_e32 v231, v231, v109
	v_add_f32_e32 v232, v232, v113
	v_add_f32_e32 v233, v233, v117
	v_add_f32_e32 v234, v234, v121
	v_add_f32_e32 v235, v235, v125
	v_add_f32_e32 v236, v236, v129
	v_add_f32_e32 v237, v237, v181
	v_add_f32_e32 v238, v238, v185
	v_add_f32_e32 v239, v239, v189
	v_add_f32_e32 v240, v240, v193
	v_add_f32_e32 v241, v241, v197
	v_add_f32_e32 v242, v242, v201
	v_add_f32_e32 v243, v243, v205
	v_add_f32_e32 v244, v244, v209
	v_pk_mul_f32 v[2:3], v[2:3], v[214:215]
	v_pk_mul_f32 v[4:5], v[4:5], v[216:217]
	v_pk_mul_f32 v[6:7], v[6:7], v[214:215]
	v_pk_mul_f32 v[8:9], v[8:9], v[216:217]
	v_pk_mul_f32 v[10:11], v[10:11], v[214:215]
	v_pk_mul_f32 v[12:13], v[12:13], v[216:217]
	v_pk_mul_f32 v[14:15], v[14:15], v[214:215]
	v_pk_mul_f32 v[16:17], v[16:17], v[216:217]
	v_pk_mul_f32 v[18:19], v[18:19], v[214:215]
	v_pk_mul_f32 v[20:21], v[20:21], v[216:217]
	v_pk_mul_f32 v[22:23], v[22:23], v[214:215]
	v_pk_mul_f32 v[24:25], v[24:25], v[216:217]
	v_pk_mul_f32 v[26:27], v[26:27], v[214:215]
	v_pk_mul_f32 v[28:29], v[28:29], v[216:217]
	v_pk_mul_f32 v[30:31], v[30:31], v[214:215]
	v_pk_mul_f32 v[32:33], v[32:33], v[216:217]
	v_pk_mul_f32 v[34:35], v[34:35], v[214:215]
	v_pk_mul_f32 v[36:37], v[36:37], v[216:217]
	v_pk_mul_f32 v[38:39], v[38:39], v[214:215]
	v_pk_mul_f32 v[40:41], v[40:41], v[216:217]
	v_pk_mul_f32 v[42:43], v[42:43], v[214:215]
	v_pk_mul_f32 v[44:45], v[44:45], v[216:217]
	v_pk_mul_f32 v[46:47], v[46:47], v[214:215]
	v_pk_mul_f32 v[48:49], v[48:49], v[216:217]
	v_pk_mul_f32 v[50:51], v[50:51], v[214:215]
	v_pk_mul_f32 v[52:53], v[52:53], v[216:217]
	v_pk_mul_f32 v[54:55], v[54:55], v[214:215]
	v_pk_mul_f32 v[56:57], v[56:57], v[216:217]
	v_pk_mul_f32 v[58:59], v[58:59], v[214:215]
	v_pk_mul_f32 v[60:61], v[60:61], v[216:217]
	v_pk_mul_f32 v[62:63], v[62:63], v[214:215]
	v_pk_mul_f32 v[64:65], v[64:65], v[216:217]
	v_cvt_pk_bf16_f32 v98, v2, v3
	v_cvt_pk_bf16_f32 v99, v4, v5
	v_cvt_pk_bf16_f32 v102, v6, v7
	v_cvt_pk_bf16_f32 v103, v8, v9
	v_cvt_pk_bf16_f32 v106, v10, v11
	v_cvt_pk_bf16_f32 v107, v12, v13
	v_cvt_pk_bf16_f32 v110, v14, v15
	v_cvt_pk_bf16_f32 v111, v16, v17
	v_cvt_pk_bf16_f32 v114, v18, v19
	v_cvt_pk_bf16_f32 v115, v20, v21
	v_cvt_pk_bf16_f32 v118, v22, v23
	v_cvt_pk_bf16_f32 v119, v24, v25
	v_cvt_pk_bf16_f32 v122, v26, v27
	v_cvt_pk_bf16_f32 v123, v28, v29
	v_cvt_pk_bf16_f32 v126, v30, v31
	v_cvt_pk_bf16_f32 v127, v32, v33
	v_cvt_pk_bf16_f32 v178, v34, v35
	v_cvt_pk_bf16_f32 v179, v36, v37
	v_cvt_pk_bf16_f32 v182, v38, v39
	v_cvt_pk_bf16_f32 v183, v40, v41
	v_cvt_pk_bf16_f32 v186, v42, v43
	v_cvt_pk_bf16_f32 v187, v44, v45
	v_cvt_pk_bf16_f32 v190, v46, v47
	v_cvt_pk_bf16_f32 v191, v48, v49
	v_cvt_pk_bf16_f32 v194, v50, v51
	v_cvt_pk_bf16_f32 v195, v52, v53
	v_cvt_pk_bf16_f32 v198, v54, v55
	v_cvt_pk_bf16_f32 v199, v56, v57
	v_cvt_pk_bf16_f32 v202, v58, v59
	v_cvt_pk_bf16_f32 v203, v60, v61
	v_cvt_pk_bf16_f32 v206, v62, v63
	v_cvt_pk_bf16_f32 v207, v64, v65
	v_readlane_b32 s56, v248, 13
	v_readlane_b32 s57, v248, 14
	s_mul_i32 s0, s51, 0xa000
	s_lshl_b32 s1, s2, 2
	s_add_i32 s0, s0, s1
	s_add_u32 s56, s56, s0
	s_addc_u32 s57, s57, 0
	s_mul_i32 s0, s2, 0x880
	s_add_u32 s58, s8, s0
	s_addc_u32 s59, s9, 0
	v_mov_b32_e32 v228, v224
	global_store_dwordx2 v228, v[98:99], s[58:59] sc0 sc1
	v_add_u32_e32 v228, 0x4400, v228
	global_store_dwordx2 v228, v[102:103], s[58:59] sc0 sc1
	v_add_u32_e32 v228, 0x4400, v228
	global_store_dwordx2 v228, v[106:107], s[58:59] sc0 sc1
	v_add_u32_e32 v228, 0x4400, v228
	global_store_dwordx2 v228, v[110:111], s[58:59] sc0 sc1
	v_add_u32_e32 v228, 0x4400, v228
	global_store_dwordx2 v228, v[114:115], s[58:59] sc0 sc1
	v_add_u32_e32 v228, 0x4400, v228
	global_store_dwordx2 v228, v[118:119], s[58:59] sc0 sc1
	v_add_u32_e32 v228, 0x4400, v228
	global_store_dwordx2 v228, v[122:123], s[58:59] sc0 sc1
	v_add_u32_e32 v228, 0x4400, v228
	global_store_dwordx2 v228, v[126:127], s[58:59] sc0 sc1
	v_add_u32_e32 v228, 0x4400, v228
	global_store_dwordx2 v228, v[178:179], s[58:59] sc0 sc1
	v_add_u32_e32 v228, 0x4400, v228
	global_store_dwordx2 v228, v[182:183], s[58:59] sc0 sc1
	v_add_u32_e32 v228, 0x4400, v228
	global_store_dwordx2 v228, v[186:187], s[58:59] sc0 sc1
	v_add_u32_e32 v228, 0x4400, v228
	global_store_dwordx2 v228, v[190:191], s[58:59] sc0 sc1
	v_add_u32_e32 v228, 0x4400, v228
	global_store_dwordx2 v228, v[194:195], s[58:59] sc0 sc1
	v_add_u32_e32 v228, 0x4400, v228
	global_store_dwordx2 v228, v[198:199], s[58:59] sc0 sc1
	v_add_u32_e32 v228, 0x4400, v228
	global_store_dwordx2 v228, v[202:203], s[58:59] sc0 sc1
	v_add_u32_e32 v228, 0x4400, v228
	global_store_dwordx2 v228, v[206:207], s[58:59] sc0 sc1
	v_add_f32_dpp v229, v229, v229 quad_perm:[1,0,3,2] row_mask:0xf bank_mask:0xf
	v_add_f32_dpp v230, v230, v230 quad_perm:[1,0,3,2] row_mask:0xf bank_mask:0xf
	v_add_f32_dpp v231, v231, v231 quad_perm:[1,0,3,2] row_mask:0xf bank_mask:0xf
	v_add_f32_dpp v232, v232, v232 quad_perm:[1,0,3,2] row_mask:0xf bank_mask:0xf
	v_add_f32_dpp v233, v233, v233 quad_perm:[1,0,3,2] row_mask:0xf bank_mask:0xf
	v_add_f32_dpp v234, v234, v234 quad_perm:[1,0,3,2] row_mask:0xf bank_mask:0xf
	v_add_f32_dpp v235, v235, v235 quad_perm:[1,0,3,2] row_mask:0xf bank_mask:0xf
	v_add_f32_dpp v236, v236, v236 quad_perm:[1,0,3,2] row_mask:0xf bank_mask:0xf
	v_add_f32_dpp v237, v237, v237 quad_perm:[1,0,3,2] row_mask:0xf bank_mask:0xf
	v_add_f32_dpp v238, v238, v238 quad_perm:[1,0,3,2] row_mask:0xf bank_mask:0xf
	v_add_f32_dpp v239, v239, v239 quad_perm:[1,0,3,2] row_mask:0xf bank_mask:0xf
	v_add_f32_dpp v240, v240, v240 quad_perm:[1,0,3,2] row_mask:0xf bank_mask:0xf
	v_add_f32_dpp v241, v241, v241 quad_perm:[1,0,3,2] row_mask:0xf bank_mask:0xf
	v_add_f32_dpp v242, v242, v242 quad_perm:[1,0,3,2] row_mask:0xf bank_mask:0xf
	v_add_f32_dpp v243, v243, v243 quad_perm:[1,0,3,2] row_mask:0xf bank_mask:0xf
	v_add_f32_dpp v244, v244, v244 quad_perm:[1,0,3,2] row_mask:0xf bank_mask:0xf
	v_add_f32_dpp v229, v229, v229 quad_perm:[2,3,0,1] row_mask:0xf bank_mask:0xf
	v_add_f32_dpp v230, v230, v230 quad_perm:[2,3,0,1] row_mask:0xf bank_mask:0xf
	v_add_f32_dpp v231, v231, v231 quad_perm:[2,3,0,1] row_mask:0xf bank_mask:0xf
	v_add_f32_dpp v232, v232, v232 quad_perm:[2,3,0,1] row_mask:0xf bank_mask:0xf
	v_add_f32_dpp v233, v233, v233 quad_perm:[2,3,0,1] row_mask:0xf bank_mask:0xf
	v_add_f32_dpp v234, v234, v234 quad_perm:[2,3,0,1] row_mask:0xf bank_mask:0xf
	v_add_f32_dpp v235, v235, v235 quad_perm:[2,3,0,1] row_mask:0xf bank_mask:0xf
	v_add_f32_dpp v236, v236, v236 quad_perm:[2,3,0,1] row_mask:0xf bank_mask:0xf
	v_add_f32_dpp v237, v237, v237 quad_perm:[2,3,0,1] row_mask:0xf bank_mask:0xf
	v_add_f32_dpp v238, v238, v238 quad_perm:[2,3,0,1] row_mask:0xf bank_mask:0xf
	v_add_f32_dpp v239, v239, v239 quad_perm:[2,3,0,1] row_mask:0xf bank_mask:0xf
	v_add_f32_dpp v240, v240, v240 quad_perm:[2,3,0,1] row_mask:0xf bank_mask:0xf
	v_add_f32_dpp v241, v241, v241 quad_perm:[2,3,0,1] row_mask:0xf bank_mask:0xf
	v_add_f32_dpp v242, v242, v242 quad_perm:[2,3,0,1] row_mask:0xf bank_mask:0xf
	v_add_f32_dpp v243, v243, v243 quad_perm:[2,3,0,1] row_mask:0xf bank_mask:0xf
	v_add_f32_dpp v244, v244, v244 quad_perm:[2,3,0,1] row_mask:0xf bank_mask:0xf
	v_add_f32_dpp v229, v229, v229 row_ror:4 row_mask:0xf bank_mask:0xf
	v_add_f32_dpp v230, v230, v230 row_ror:4 row_mask:0xf bank_mask:0xf
	v_add_f32_dpp v231, v231, v231 row_ror:4 row_mask:0xf bank_mask:0xf
	v_add_f32_dpp v232, v232, v232 row_ror:4 row_mask:0xf bank_mask:0xf
	v_add_f32_dpp v233, v233, v233 row_ror:4 row_mask:0xf bank_mask:0xf
	v_add_f32_dpp v234, v234, v234 row_ror:4 row_mask:0xf bank_mask:0xf
	v_add_f32_dpp v235, v235, v235 row_ror:4 row_mask:0xf bank_mask:0xf
	v_add_f32_dpp v236, v236, v236 row_ror:4 row_mask:0xf bank_mask:0xf
	v_add_f32_dpp v237, v237, v237 row_ror:4 row_mask:0xf bank_mask:0xf
	v_add_f32_dpp v238, v238, v238 row_ror:4 row_mask:0xf bank_mask:0xf
	v_add_f32_dpp v239, v239, v239 row_ror:4 row_mask:0xf bank_mask:0xf
	v_add_f32_dpp v240, v240, v240 row_ror:4 row_mask:0xf bank_mask:0xf
	v_add_f32_dpp v241, v241, v241 row_ror:4 row_mask:0xf bank_mask:0xf
	v_add_f32_dpp v242, v242, v242 row_ror:4 row_mask:0xf bank_mask:0xf
	v_add_f32_dpp v243, v243, v243 row_ror:4 row_mask:0xf bank_mask:0xf
	v_add_f32_dpp v244, v244, v244 row_ror:4 row_mask:0xf bank_mask:0xf
	v_add_f32_dpp v229, v229, v229 row_ror:8 row_mask:0xf bank_mask:0xf
	v_add_f32_dpp v230, v230, v230 row_ror:8 row_mask:0xf bank_mask:0xf
	v_add_f32_dpp v231, v231, v231 row_ror:8 row_mask:0xf bank_mask:0xf
	v_add_f32_dpp v232, v232, v232 row_ror:8 row_mask:0xf bank_mask:0xf
	v_add_f32_dpp v233, v233, v233 row_ror:8 row_mask:0xf bank_mask:0xf
	v_add_f32_dpp v234, v234, v234 row_ror:8 row_mask:0xf bank_mask:0xf
	v_add_f32_dpp v235, v235, v235 row_ror:8 row_mask:0xf bank_mask:0xf
	v_add_f32_dpp v236, v236, v236 row_ror:8 row_mask:0xf bank_mask:0xf
	v_add_f32_dpp v237, v237, v237 row_ror:8 row_mask:0xf bank_mask:0xf
	v_add_f32_dpp v238, v238, v238 row_ror:8 row_mask:0xf bank_mask:0xf
	v_add_f32_dpp v239, v239, v239 row_ror:8 row_mask:0xf bank_mask:0xf
	v_add_f32_dpp v240, v240, v240 row_ror:8 row_mask:0xf bank_mask:0xf
	v_add_f32_dpp v241, v241, v241 row_ror:8 row_mask:0xf bank_mask:0xf
	v_add_f32_dpp v242, v242, v242 row_ror:8 row_mask:0xf bank_mask:0xf
	v_add_f32_dpp v243, v243, v243 row_ror:8 row_mask:0xf bank_mask:0xf
	v_add_f32_dpp v244, v244, v244 row_ror:8 row_mask:0xf bank_mask:0xf
	v_add_f32_dpp v229, v229, v229 row_bcast:15 row_mask:0xa bank_mask:0xf
	v_add_f32_dpp v230, v230, v230 row_bcast:15 row_mask:0xa bank_mask:0xf
	v_add_f32_dpp v231, v231, v231 row_bcast:15 row_mask:0xa bank_mask:0xf
	v_add_f32_dpp v232, v232, v232 row_bcast:15 row_mask:0xa bank_mask:0xf
	v_add_f32_dpp v233, v233, v233 row_bcast:15 row_mask:0xa bank_mask:0xf
	v_add_f32_dpp v234, v234, v234 row_bcast:15 row_mask:0xa bank_mask:0xf
	v_add_f32_dpp v235, v235, v235 row_bcast:15 row_mask:0xa bank_mask:0xf
	v_add_f32_dpp v236, v236, v236 row_bcast:15 row_mask:0xa bank_mask:0xf
	v_add_f32_dpp v237, v237, v237 row_bcast:15 row_mask:0xa bank_mask:0xf
	v_add_f32_dpp v238, v238, v238 row_bcast:15 row_mask:0xa bank_mask:0xf
	v_add_f32_dpp v239, v239, v239 row_bcast:15 row_mask:0xa bank_mask:0xf
	v_add_f32_dpp v240, v240, v240 row_bcast:15 row_mask:0xa bank_mask:0xf
	v_add_f32_dpp v241, v241, v241 row_bcast:15 row_mask:0xa bank_mask:0xf
	v_add_f32_dpp v242, v242, v242 row_bcast:15 row_mask:0xa bank_mask:0xf
	v_add_f32_dpp v243, v243, v243 row_bcast:15 row_mask:0xa bank_mask:0xf
	v_add_f32_dpp v244, v244, v244 row_bcast:15 row_mask:0xa bank_mask:0xf
	s_mov_b64 s[40:41], exec
	s_mov_b32 s0, 0x80000000
	s_mov_b32 s1, 0x80000000
	s_mov_b64 exec, s[0:1]
	global_store_dword v226, v229, s[56:57]
	global_store_dword v226, v230, s[56:57] offset:32
	global_store_dword v226, v231, s[56:57] offset:64
	global_store_dword v226, v232, s[56:57] offset:96
	global_store_dword v226, v233, s[56:57] offset:128
	global_store_dword v226, v234, s[56:57] offset:160
	global_store_dword v226, v235, s[56:57] offset:192
	global_store_dword v226, v236, s[56:57] offset:224
	global_store_dword v226, v237, s[56:57] offset:256
	global_store_dword v226, v238, s[56:57] offset:288
	global_store_dword v226, v239, s[56:57] offset:320
	global_store_dword v226, v240, s[56:57] offset:352
	global_store_dword v226, v241, s[56:57] offset:384
	global_store_dword v226, v242, s[56:57] offset:416
	global_store_dword v226, v243, s[56:57] offset:448
	global_store_dword v226, v244, s[56:57] offset:480
	s_mov_b64 exec, s[40:41]
	s_branch .LBB0_122

.LBB0_165:
	ds_read_b128 v[204:207], v138
	ds_read_b128 v[208:211], v138 offset:32
	ds_read_b128 v[212:215], v138 offset:4608
	ds_read_b128 v[216:219], v138 offset:4640
	ds_read_b128 v[220:223], v139 offset:36864
	ds_read_b128 v[224:227], v139 offset:36896
	ds_read_b128 v[228:231], v139 offset:41472
	ds_read_b128 v[232:235], v139 offset:41504
	s_waitcnt vmcnt(15)
	ds_write_b128 v199, v[94:97] offset:18432
	buffer_load_dwordx4 v[94:97], v200, s[44:47], s0 offen
	s_waitcnt lgkmcnt(4)
	v_mfma_f32_32x32x16_bf16 v[50:65], v[204:207], v[220:223], v[50:65]
	s_add_u32 s24, s20, s0
	s_addc_u32 s22, s21, s1
	s_and_b32 s25, s22, 0xffff
	s_waitcnt lgkmcnt(2)
	v_mfma_f32_32x32x16_bf16 v[34:49], v[204:207], v[228:231], v[34:49]
	s_waitcnt vmcnt(15)
	ds_write_b128 v199, v[90:93] offset:55296
	buffer_load_dwordx4 v[90:93], v200, s[24:27], 0 offen
	v_mfma_f32_32x32x16_bf16 v[18:33], v[212:215], v[220:223], v[18:33]
	v_mfma_f32_32x32x16_bf16 v[2:17], v[212:215], v[228:231], v[2:17]
	s_add_i32 s22, s0, 0x11000
	ds_read_b128 v[204:207], v138 offset:64
	ds_read_b128 v[212:215], v138 offset:4672
	ds_read_b128 v[220:223], v139 offset:36928
	ds_read_b128 v[228:231], v139 offset:41536
	s_waitcnt vmcnt(15)
	ds_write_b128 v199, v[86:89] offset:23040
	buffer_load_dwordx4 v[86:89], v200, s[44:47], s22 offen
	v_mfma_f32_32x32x16_bf16 v[50:65], v[208:211], v[224:227], v[50:65]
	s_waitcnt lgkmcnt(7)
	v_mfma_f32_32x32x16_bf16 v[34:49], v[208:211], v[232:235], v[34:49]
	s_waitcnt vmcnt(15)
	ds_write_b128 v199, v[82:85] offset:59904
	buffer_load_dwordx4 v[82:85], v200, s[24:27], s33 offen
	v_mfma_f32_32x32x16_bf16 v[18:33], v[216:219], v[224:227], v[18:33]
	v_mfma_f32_32x32x16_bf16 v[2:17], v[216:219], v[232:235], v[2:17]
	s_add_i32 s22, s0, 0x22000
	ds_read_b128 v[208:211], v138 offset:96
	ds_read_b128 v[216:219], v138 offset:4704
	ds_read_b128 v[224:227], v139 offset:36960
	ds_read_b128 v[232:235], v139 offset:41568
	s_waitcnt vmcnt(15)
	ds_write_b128 v199, v[78:81] offset:27648
	buffer_load_dwordx4 v[78:81], v200, s[44:47], s22 offen
	s_waitcnt lgkmcnt(8)
	v_mfma_f32_32x32x16_bf16 v[50:65], v[204:207], v[220:223], v[50:65]
	s_waitcnt lgkmcnt(7)
	v_mfma_f32_32x32x16_bf16 v[34:49], v[204:207], v[228:231], v[34:49]
	s_waitcnt vmcnt(15)
	ds_write_b128 v199, v[74:77] offset:64512
	buffer_load_dwordx4 v[74:77], v200, s[24:27], s29 offen
	v_mfma_f32_32x32x16_bf16 v[18:33], v[212:215], v[220:223], v[18:33]
	v_mfma_f32_32x32x16_bf16 v[2:17], v[212:215], v[228:231], v[2:17]
	s_add_i32 s22, s0, 0x33000
	s_waitcnt vmcnt(15)
	ds_write_b128 v199, v[70:73] offset:32256
	buffer_load_dwordx4 v[70:73], v200, s[44:47], s22 offen
	s_waitcnt lgkmcnt(4)
	v_mfma_f32_32x32x16_bf16 v[50:65], v[208:211], v[224:227], v[50:65]
	s_waitcnt lgkmcnt(3)
	v_mfma_f32_32x32x16_bf16 v[34:49], v[208:211], v[232:235], v[34:49]
	s_waitcnt vmcnt(15)
	ds_write_b128 v202, v[66:69] offset:13824
	buffer_load_dwordx4 v[66:69], v200, s[24:27], s3 offen
	v_mfma_f32_32x32x16_bf16 v[18:33], v[216:219], v[224:227], v[18:33]
	v_mfma_f32_32x32x16_bf16 v[2:17], v[216:219], v[232:235], v[2:17]
	s_min_u32 s22, s98, 11
	s_lshl_b32 s22, s22, 7
	s_add_i32 s23, s22, 0x200
	s_waitcnt lgkmcnt(0)
	s_barrier
	s_cmp_eq_u32 s98, 12
	s_cbranch_scc1 .Llast_165
	ds_read_b128 v[204:207], v138 offset:18432
	ds_read_b128 v[208:211], v138 offset:18464
	ds_read_b128 v[212:215], v138 offset:23040
	ds_read_b128 v[216:219], v138 offset:23072
	ds_read_b128 v[220:223], v139 offset:55296
	ds_read_b128 v[224:227], v139 offset:55328
	ds_read_b128 v[228:231], v139 offset:59904
	ds_read_b128 v[232:235], v139 offset:59936
	s_waitcnt vmcnt(15)
	ds_write_b128 v199, v[102:105]
	buffer_load_dwordx4 v[102:105], v200, s[44:47], s23 offen
	s_waitcnt lgkmcnt(4)
	v_mfma_f32_32x32x16_bf16 v[50:65], v[204:207], v[220:223], v[50:65]
	s_add_u32 s24, s56, s23
	s_addc_u32 s23, s2, 0
	s_and_b32 s25, s23, 0xffff
	s_waitcnt lgkmcnt(2)
	v_mfma_f32_32x32x16_bf16 v[34:49], v[204:207], v[228:231], v[34:49]
	s_waitcnt vmcnt(15)
	ds_write_b128 v199, v[98:101] offset:36864
	buffer_load_dwordx4 v[98:101], v200, s[24:27], 0 offen
	v_mfma_f32_32x32x16_bf16 v[18:33], v[212:215], v[220:223], v[18:33]
	v_mfma_f32_32x32x16_bf16 v[2:17], v[212:215], v[228:231], v[2:17]
	s_add_i32 s23, s22, 0x11200
	ds_read_b128 v[204:207], v138 offset:18496
	ds_read_b128 v[212:215], v138 offset:23104
	ds_read_b128 v[220:223], v139 offset:55360
	ds_read_b128 v[228:231], v139 offset:59968
	s_waitcnt vmcnt(15)
	ds_write_b128 v199, v[106:109] offset:4608
	buffer_load_dwordx4 v[106:109], v200, s[44:47], s23 offen
	v_mfma_f32_32x32x16_bf16 v[50:65], v[208:211], v[224:227], v[50:65]
	s_waitcnt lgkmcnt(7)
	v_mfma_f32_32x32x16_bf16 v[34:49], v[208:211], v[232:235], v[34:49]
	s_waitcnt vmcnt(15)
	ds_write_b128 v199, v[110:113] offset:41472
	buffer_load_dwordx4 v[110:113], v200, s[24:27], s33 offen
	v_mfma_f32_32x32x16_bf16 v[18:33], v[216:219], v[224:227], v[18:33]
	v_mfma_f32_32x32x16_bf16 v[2:17], v[216:219], v[232:235], v[2:17]
	s_add_i32 s23, s22, 0x22200
	ds_read_b128 v[208:211], v138 offset:18528
	ds_read_b128 v[216:219], v138 offset:23136
	ds_read_b128 v[224:227], v139 offset:55392
	ds_read_b128 v[232:235], v139 offset:60000
	s_waitcnt vmcnt(15)
	ds_write_b128 v199, v[114:117] offset:9216
	buffer_load_dwordx4 v[114:117], v200, s[44:47], s23 offen
	s_waitcnt lgkmcnt(8)
	v_mfma_f32_32x32x16_bf16 v[50:65], v[204:207], v[220:223], v[50:65]
	s_waitcnt lgkmcnt(7)
	v_mfma_f32_32x32x16_bf16 v[34:49], v[204:207], v[228:231], v[34:49]
	s_waitcnt vmcnt(15)
	ds_write_b128 v199, v[118:121] offset:46080
	buffer_load_dwordx4 v[118:121], v200, s[24:27], s29 offen
	v_mfma_f32_32x32x16_bf16 v[18:33], v[212:215], v[220:223], v[18:33]
	v_mfma_f32_32x32x16_bf16 v[2:17], v[212:215], v[228:231], v[2:17]
	s_add_i32 s22, s22, 0x33200
	s_waitcnt vmcnt(15)
	ds_write_b128 v199, v[122:125] offset:13824
	buffer_load_dwordx4 v[122:125], v200, s[44:47], s22 offen
	s_waitcnt lgkmcnt(4)
	v_mfma_f32_32x32x16_bf16 v[50:65], v[208:211], v[224:227], v[50:65]
	s_waitcnt lgkmcnt(3)
	v_mfma_f32_32x32x16_bf16 v[34:49], v[208:211], v[232:235], v[34:49]
	s_waitcnt vmcnt(15)
	ds_write_b128 v199, v[126:129] offset:50688
	buffer_load_dwordx4 v[126:129], v200, s[24:27], s3 offen
	v_mfma_f32_32x32x16_bf16 v[18:33], v[216:219], v[224:227], v[18:33]
	v_mfma_f32_32x32x16_bf16 v[2:17], v[216:219], v[232:235], v[2:17]
	s_add_i32 s98, s98, 2
	s_add_u32 s0, s0, 0x100
	s_addc_u32 s1, s1, 0
	s_cmp_lt_u32 s98, 14
	s_waitcnt lgkmcnt(0)
	s_barrier
	s_cbranch_scc1 .LBB0_165
	s_branch .Ltail_165
.Llast_165:
	ds_read_b128 v[204:207], v138 offset:18432
	ds_read_b128 v[208:211], v138 offset:18464
	ds_read_b128 v[212:215], v138 offset:23040
	ds_read_b128 v[216:219], v138 offset:23072
	ds_read_b128 v[220:223], v139 offset:55296
	ds_read_b128 v[224:227], v139 offset:55328
	ds_read_b128 v[228:231], v139 offset:59904
	ds_read_b128 v[232:235], v139 offset:59936
	s_waitcnt vmcnt(15)
	ds_write_b128 v199, v[102:105]
	s_waitcnt lgkmcnt(4)
	v_mfma_f32_32x32x16_bf16 v[50:65], v[204:207], v[220:223], v[50:65]
	s_add_u32 s24, s56, s23
	s_addc_u32 s23, s2, 0
	s_and_b32 s25, s23, 0xffff
	s_waitcnt lgkmcnt(2)
	v_mfma_f32_32x32x16_bf16 v[34:49], v[204:207], v[228:231], v[34:49]
	s_waitcnt vmcnt(14)
	ds_write_b128 v199, v[98:101] offset:36864
	v_mfma_f32_32x32x16_bf16 v[18:33], v[212:215], v[220:223], v[18:33]
	v_mfma_f32_32x32x16_bf16 v[2:17], v[212:215], v[228:231], v[2:17]
	s_add_i32 s23, s22, 0x11200
	ds_read_b128 v[204:207], v138 offset:18496
	ds_read_b128 v[212:215], v138 offset:23104
	ds_read_b128 v[220:223], v139 offset:55360
	ds_read_b128 v[228:231], v139 offset:59968
	s_waitcnt vmcnt(13)
	ds_write_b128 v199, v[106:109] offset:4608
	v_mfma_f32_32x32x16_bf16 v[50:65], v[208:211], v[224:227], v[50:65]
	s_waitcnt lgkmcnt(7)
	v_mfma_f32_32x32x16_bf16 v[34:49], v[208:211], v[232:235], v[34:49]
	s_waitcnt vmcnt(12)
	ds_write_b128 v199, v[110:113] offset:41472
	v_mfma_f32_32x32x16_bf16 v[18:33], v[216:219], v[224:227], v[18:33]
	v_mfma_f32_32x32x16_bf16 v[2:17], v[216:219], v[232:235], v[2:17]
	s_add_i32 s23, s22, 0x22200
	ds_read_b128 v[208:211], v138 offset:18528
	ds_read_b128 v[216:219], v138 offset:23136
	ds_read_b128 v[224:227], v139 offset:55392
	ds_read_b128 v[232:235], v139 offset:60000
	s_waitcnt vmcnt(11)
	ds_write_b128 v199, v[114:117] offset:9216
	s_waitcnt lgkmcnt(8)
	v_mfma_f32_32x32x16_bf16 v[50:65], v[204:207], v[220:223], v[50:65]
	s_waitcnt lgkmcnt(7)
	v_mfma_f32_32x32x16_bf16 v[34:49], v[204:207], v[228:231], v[34:49]
	s_waitcnt vmcnt(10)
	ds_write_b128 v199, v[118:121] offset:46080
	v_mfma_f32_32x32x16_bf16 v[18:33], v[212:215], v[220:223], v[18:33]
	v_mfma_f32_32x32x16_bf16 v[2:17], v[212:215], v[228:231], v[2:17]
	s_add_i32 s22, s22, 0x33200
	s_waitcnt vmcnt(9)
	ds_write_b128 v199, v[122:125] offset:13824
	s_waitcnt lgkmcnt(4)
	v_mfma_f32_32x32x16_bf16 v[50:65], v[208:211], v[224:227], v[50:65]
	s_waitcnt lgkmcnt(3)
	v_mfma_f32_32x32x16_bf16 v[34:49], v[208:211], v[232:235], v[34:49]
	s_waitcnt vmcnt(8)
	ds_write_b128 v199, v[126:129] offset:50688
	v_mfma_f32_32x32x16_bf16 v[18:33], v[216:219], v[224:227], v[18:33]
	v_mfma_f32_32x32x16_bf16 v[2:17], v[216:219], v[232:235], v[2:17]
	s_add_i32 s98, s98, 2
	s_add_u32 s0, s0, 0x100
	s_addc_u32 s1, s1, 0
	s_cmp_lt_u32 s98, 14
	s_waitcnt lgkmcnt(0)
	s_barrier
	s_branch .Ltail_165
.Ltail_165:
	s_waitcnt vmcnt(6)
	ds_read_b128 v[98:101], v138
	ds_read_b128 v[102:105], v139 offset:36864
	s_waitcnt vmcnt(5)
	ds_read_b128 v[106:109], v138 offset:32
	s_waitcnt vmcnt(4)
	ds_read_b128 v[110:113], v139 offset:36896
	s_waitcnt vmcnt(3)
	ds_read_b128 v[114:117], v139 offset:41472
	s_waitcnt vmcnt(2)
	ds_read_b128 v[118:121], v138 offset:4608
	s_waitcnt vmcnt(1)
	ds_read_b128 v[122:125], v138 offset:4640
	s_waitcnt vmcnt(0)
	ds_read_b128 v[126:129], v139 offset:41504
	ds_write_b128 v199, v[94:97] offset:18432
	s_waitcnt lgkmcnt(7)
	v_mfma_f32_32x32x16_bf16 v[50:65], v[98:101], v[102:105], v[50:65]
	s_waitcnt lgkmcnt(4)
	v_mfma_f32_32x32x16_bf16 v[34:49], v[98:101], v[114:117], v[34:49]
	s_waitcnt lgkmcnt(3)
	v_mfma_f32_32x32x16_bf16 v[18:33], v[118:121], v[102:105], v[18:33]
	ds_write_b128 v199, v[90:93] offset:55296
	v_mfma_f32_32x32x16_bf16 v[2:17], v[118:121], v[114:117], v[2:17]
	ds_read_b128 v[90:93], v138 offset:64
	ds_read_b128 v[94:97], v138 offset:4672
	ds_read_b128 v[98:101], v139 offset:36928
	ds_read_b128 v[102:105], v139 offset:41536
	v_mfma_f32_32x32x16_bf16 v[50:65], v[106:109], v[110:113], v[50:65]
	ds_write_b128 v199, v[86:89] offset:23040
	s_waitcnt lgkmcnt(7)
	v_mfma_f32_32x32x16_bf16 v[34:49], v[106:109], v[126:129], v[34:49]
	v_mfma_f32_32x32x16_bf16 v[18:33], v[122:125], v[110:113], v[18:33]
	ds_write_b128 v199, v[82:85] offset:59904
	v_mfma_f32_32x32x16_bf16 v[2:17], v[122:125], v[126:129], v[2:17]
	ds_read_b128 v[82:85], v138 offset:96
	ds_read_b128 v[86:89], v138 offset:4704
	ds_read_b128 v[106:109], v139 offset:36960
	ds_read_b128 v[110:113], v139 offset:41568
	s_waitcnt lgkmcnt(7)
	v_mfma_f32_32x32x16_bf16 v[50:65], v[90:93], v[98:101], v[50:65]
	ds_write_b128 v199, v[78:81] offset:27648
	s_waitcnt lgkmcnt(7)
	v_mfma_f32_32x32x16_bf16 v[34:49], v[90:93], v[102:105], v[34:49]
	v_mfma_f32_32x32x16_bf16 v[18:33], v[94:97], v[98:101], v[18:33]
	ds_write_b128 v199, v[74:77] offset:64512
	v_mfma_f32_32x32x16_bf16 v[2:17], v[94:97], v[102:105], v[2:17]
	s_waitcnt lgkmcnt(3)
	v_mfma_f32_32x32x16_bf16 v[50:65], v[82:85], v[106:109], v[50:65]
	ds_write_b128 v199, v[70:73] offset:32256
	s_waitcnt lgkmcnt(3)
	v_mfma_f32_32x32x16_bf16 v[34:49], v[82:85], v[110:113], v[34:49]
	v_mfma_f32_32x32x16_bf16 v[18:33], v[86:89], v[106:109], v[18:33]
	ds_write_b128 v202, v[66:69] offset:13824
	v_mfma_f32_32x32x16_bf16 v[2:17], v[86:89], v[110:113], v[2:17]
	s_waitcnt lgkmcnt(0)
	s_barrier
	ds_read_b128 v[66:69], v138 offset:18432
	ds_read_b128 v[70:73], v139 offset:55296
	ds_read_b128 v[74:77], v138 offset:18464
	ds_read_b128 v[78:81], v139 offset:55328
	ds_read_b128 v[82:85], v139 offset:59904
	ds_read_b128 v[86:89], v138 offset:23040
	ds_read_b128 v[90:93], v138 offset:23072
	ds_read_b128 v[94:97], v139 offset:59936
	s_waitcnt lgkmcnt(6)
	v_mfma_f32_32x32x16_bf16 v[50:65], v[66:69], v[70:73], v[50:65]
	s_waitcnt lgkmcnt(3)
	v_mfma_f32_32x32x16_bf16 v[34:49], v[66:69], v[82:85], v[34:49]
	s_waitcnt lgkmcnt(2)
	v_mfma_f32_32x32x16_bf16 v[18:33], v[86:89], v[70:73], v[18:33]
	v_mfma_f32_32x32x16_bf16 v[2:17], v[86:89], v[82:85], v[2:17]
	ds_read_b128 v[66:69], v138 offset:18496
	ds_read_b128 v[70:73], v138 offset:23104
	ds_read_b128 v[82:85], v139 offset:55360
	ds_read_b128 v[86:89], v139 offset:59968
	v_mfma_f32_32x32x16_bf16 v[50:65], v[74:77], v[78:81], v[50:65]
	s_waitcnt lgkmcnt(4)
	v_mfma_f32_32x32x16_bf16 v[34:49], v[74:77], v[94:97], v[34:49]
	v_mfma_f32_32x32x16_bf16 v[18:33], v[90:93], v[78:81], v[18:33]
	v_mfma_f32_32x32x16_bf16 v[2:17], v[90:93], v[94:97], v[2:17]
	ds_read_b128 v[74:77], v138 offset:18528
	ds_read_b128 v[78:81], v138 offset:23136
	ds_read_b128 v[90:93], v139 offset:55392
	ds_read_b128 v[94:97], v139 offset:60000
	s_waitcnt lgkmcnt(5)
	v_mfma_f32_32x32x16_bf16 v[50:65], v[66:69], v[82:85], v[50:65]
	s_waitcnt lgkmcnt(4)
	v_mfma_f32_32x32x16_bf16 v[34:49], v[66:69], v[86:89], v[34:49]
	v_mfma_f32_32x32x16_bf16 v[18:33], v[70:73], v[82:85], v[18:33]
	v_mfma_f32_32x32x16_bf16 v[2:17], v[70:73], v[86:89], v[2:17]
	s_waitcnt lgkmcnt(1)
	v_mfma_f32_32x32x16_bf16 v[50:65], v[74:77], v[90:93], v[50:65]
	s_waitcnt lgkmcnt(0)
	v_mfma_f32_32x32x16_bf16 v[34:49], v[74:77], v[94:97], v[34:49]
	v_mfma_f32_32x32x16_bf16 v[18:33], v[78:81], v[90:93], v[18:33]
	v_mfma_f32_32x32x16_bf16 v[2:17], v[78:81], v[94:97], v[2:17]
	v_lshl_or_b32 v66, v198, 2, v201
	s_movk_i32 s0, 0x210
	v_and_or_b32 v67, v137, 64, v151
	v_mul_lo_u32 v66, v66, s0
	v_lshl_add_u32 v66, v67, 2, v66
	s_barrier
	s_nop 3
	ds_write2_b32 v66, v50, v34 offset1:32
	ds_write2_b32 v66, v51, v35 offset0:132 offset1:164
	v_add_u32_e32 v34, 0x400, v66
	ds_write2_b32 v34, v52, v36 offset0:8 offset1:40
	ds_write2_b32 v34, v53, v37 offset0:140 offset1:172
	v_add_u32_e32 v34, 0x1000, v66
	ds_write2_b32 v34, v54, v38 offset0:32 offset1:64
	ds_write2_b32 v34, v55, v39 offset0:164 offset1:196
	v_add_u32_e32 v34, 0x1400, v66
	ds_write2_b32 v34, v56, v40 offset0:40 offset1:72
	ds_write2_b32 v34, v57, v41 offset0:172 offset1:204
	v_add_u32_e32 v34, 0x2000, v66
	ds_write2_b32 v34, v58, v42 offset0:64 offset1:96
	ds_write2_b32 v34, v59, v43 offset0:196 offset1:228
	v_add_u32_e32 v34, 0x2400, v66
	ds_write2_b32 v34, v60, v44 offset0:72 offset1:104
	ds_write2_b32 v34, v61, v45 offset0:204 offset1:236
	v_add_u32_e32 v34, 0x3000, v66
	ds_write2_b32 v34, v62, v46 offset0:96 offset1:128
	v_add_u32_e32 v34, 0x3200, v66
	ds_write2_b32 v34, v63, v47 offset0:100 offset1:132
	v_add_u32_e32 v34, 0x3400, v66
	ds_write2_b32 v34, v64, v48 offset0:104 offset1:136
	v_add_u32_e32 v34, 0x3600, v66
	ds_write2_b32 v34, v65, v49 offset0:108 offset1:140
	v_add_u32_e32 v34, 0x4000, v66
	ds_write2_b32 v34, v18, v2 offset0:128 offset1:160
	v_add_u32_e32 v2, 0x4400, v66
	ds_write2_b32 v2, v19, v3 offset0:4 offset1:36
	ds_write2_b32 v2, v20, v4 offset0:136 offset1:168
	v_add_u32_e32 v2, 0x4800, v66
	ds_write2_b32 v2, v21, v5 offset0:12 offset1:44
	v_add_u32_e32 v2, 0x5000, v66
	ds_write2_b32 v2, v22, v6 offset0:160 offset1:192
	v_add_u32_e32 v2, 0x5400, v66
	ds_write2_b32 v2, v23, v7 offset0:36 offset1:68
	ds_write2_b32 v2, v24, v8 offset0:168 offset1:200
	v_add_u32_e32 v2, 0x5800, v66
	ds_write2_b32 v2, v25, v9 offset0:44 offset1:76
	v_add_u32_e32 v2, 0x6000, v66
	ds_write2_b32 v2, v26, v10 offset0:192 offset1:224
	v_add_u32_e32 v2, 0x6400, v66
	ds_write2_b32 v2, v27, v11 offset0:68 offset1:100
	ds_write2_b32 v2, v28, v12 offset0:200 offset1:232
	v_add_u32_e32 v2, 0x6800, v66
	ds_write2_b32 v2, v29, v13 offset0:76 offset1:108
	v_add_u32_e32 v2, 0x7200, v66
	ds_write2_b32 v2, v30, v14 offset0:96 offset1:128
	v_add_u32_e32 v2, 0x7400, v66
	ds_write2_b32 v2, v31, v15 offset0:100 offset1:132
	v_add_u32_e32 v2, 0x7600, v66
	ds_write2_b32 v2, v32, v16 offset0:104 offset1:136
	v_add_u32_e32 v2, 0x7800, v66
	s_cmp_lg_u32 s96, 0
	s_mov_b64 s[0:1], -1
	ds_write2_b32 v2, v33, v17 offset0:108 offset1:140
	s_waitcnt lgkmcnt(0)
	s_barrier
	ds_write_b32 v140, v135
	s_waitcnt lgkmcnt(0)
	s_barrier
	s_cbranch_scc0 .LBB0_168
	v_add_u32_e32 v2, s55, v141
	v_ashrrev_i32_e32 v3, 31, v2
	v_lshlrev_b64 v[2:3], 11, v[2:3]
	v_lshl_add_u64 v[2:3], s[10:11], 0, v[2:3]
	s_lshl_b32 s96, s51, 1
	v_lshl_add_u64 v[2:3], v[2:3], 0, s[96:97]
	v_mov_b32_e32 v135, v147
	v_or_b32_e32 v13, 0x10a00, v142
	ds_read_b32 v12, v143
	v_lshl_add_u64 v[26:27], v[2:3], 0, v[134:135]
	ds_read_b128 v[2:5], v197
	ds_read_b128 v[6:9], v197 offset:16
	ds_read_b128 v[14:17], v197 offset:32
	ds_read_b128 v[18:21], v197 offset:48
	ds_read_b128 v[22:25], v13
	s_mov_b64 s[0:1], 0x283f800
	v_lshl_add_u64 v[10:11], v[26:27], 0, s[0:1]
	s_waitcnt lgkmcnt(0)
	v_pk_fma_f32 v[2:3], v[2:3], v[12:13], v[22:23] op_sel_hi:[1,0,1]
	s_nop 0
	v_mul_f32_e32 v13, 0xbfb8aa3b, v2
	v_exp_f32_e32 v22, v13
	v_mul_f32_e32 v13, 0xbfb8aa3b, v3
	v_exp_f32_e32 v23, v13
	s_nop 0
	v_pk_add_f32 v[22:23], v[22:23], 1.0 op_sel_hi:[1,0]
	s_nop 0
	v_rcp_f32_e32 v28, v23
	s_nop 0
	v_mul_f32_e32 v30, v3, v28
	v_fma_f32 v31, -v23, v30, v3
	v_fma_f32 v13, v31, v28, v30
	v_div_fixup_f32 v3, v13, v23, v3
	v_rcp_f32_e32 v23, v22
	s_nop 0
	v_mul_f32_e32 v29, v2, v23
	v_fma_f32 v30, -v22, v29, v2
	v_fma_f32 v13, v30, v23, v29
	v_div_fixup_f32 v2, v13, v22, v2
	v_pk_fma_f32 v[4:5], v[4:5], v[12:13], v[24:25] op_sel_hi:[1,0,1]
	v_cvt_pk_bf16_f32 v2, v2, v3
	v_mul_f32_e32 v3, 0xbfb8aa3b, v4
	v_exp_f32_e32 v22, v3
	v_mul_f32_e32 v3, 0xbfb8aa3b, v5
	v_exp_f32_e32 v23, v3
	s_nop 0
	v_pk_add_f32 v[22:23], v[22:23], 1.0 op_sel_hi:[1,0]
	s_nop 0
	v_rcp_f32_e32 v13, v23
	s_nop 0
	v_mul_f32_e32 v25, v5, v13
	v_fma_f32 v28, -v23, v25, v5
	v_fma_f32 v3, v28, v13, v25
	v_div_fixup_f32 v3, v3, v23, v5
	v_rcp_f32_e32 v13, v22
	s_nop 0
	v_mul_f32_e32 v24, v4, v13
	v_fma_f32 v25, -v22, v24, v4
	v_fma_f32 v5, v25, v13, v24
	v_div_fixup_f32 v4, v5, v22, v4
	v_cvt_pk_bf16_f32 v3, v4, v3
	v_add_u32_e32 v4, 0x10a10, v142
	ds_read_b128 v[22:25], v4
	s_waitcnt lgkmcnt(0)
	v_pk_fma_f32 v[4:5], v[6:7], v[12:13], v[22:23] op_sel_hi:[1,0,1]
	s_nop 0
	v_mul_f32_e32 v6, 0xbfb8aa3b, v4
	v_mul_f32_e32 v7, 0xbfb8aa3b, v5
	v_exp_f32_e32 v6, v6
	v_exp_f32_e32 v7, v7
	s_nop 0
	v_pk_add_f32 v[6:7], v[6:7], 1.0 op_sel_hi:[1,0]
	s_nop 0
	v_rcp_f32_e32 v22, v7
	s_nop 0
	v_mul_f32_e32 v28, v5, v22
	v_fma_f32 v29, -v7, v28, v5
	v_fma_f32 v13, v29, v22, v28
	v_div_fixup_f32 v5, v13, v7, v5
	v_rcp_f32_e32 v13, v6
	s_nop 0
	v_mul_f32_e32 v23, v4, v13
	v_fma_f32 v28, -v6, v23, v4
	v_fma_f32 v7, v28, v13, v23
	v_div_fixup_f32 v4, v7, v6, v4
	v_pk_fma_f32 v[6:7], v[8:9], v[12:13], v[24:25] op_sel_hi:[1,0,1]
	v_cvt_pk_bf16_f32 v4, v4, v5
	v_mul_f32_e32 v5, 0xbfb8aa3b, v6
	v_exp_f32_e32 v8, v5
	v_mul_f32_e32 v5, 0xbfb8aa3b, v7
	v_exp_f32_e32 v9, v5
	s_nop 0
	v_pk_add_f32 v[8:9], v[8:9], 1.0 op_sel_hi:[1,0]
	s_nop 0
	v_rcp_f32_e32 v13, v9
	s_nop 0
	v_mul_f32_e32 v23, v7, v13
	v_fma_f32 v24, -v9, v23, v7
	v_fma_f32 v5, v24, v13, v23
	v_div_fixup_f32 v5, v5, v9, v7
	v_div_scale_f32 v7, s[0:1], v8, v8, v6
	v_rcp_f32_e32 v9, v7
	s_mov_b32 s0, 0x283f000
	v_fma_f32 v13, -v7, v9, 1.0
	v_fmac_f32_e32 v9, v13, v9
	v_div_scale_f32 v13, vcc, v6, v8, v6
	v_mul_f32_e32 v22, v13, v9
	v_fma_f32 v23, -v7, v22, v13
	v_fmac_f32_e32 v22, v23, v9
	v_fma_f32 v7, -v7, v22, v13
	v_div_fmas_f32 v7, v7, v9, v22
	v_div_fixup_f32 v6, v7, v8, v6
	v_cvt_pk_bf16_f32 v5, v6, v5
	v_add_co_u32_e32 v6, vcc, s0, v26
	s_nop 1
	v_addc_co_u32_e32 v7, vcc, 0, v27, vcc
	global_store_dwordx4 v[6:7], v[2:5], off offset:2048
	s_nop 1
	v_add_u32_e32 v2, 0x10a20, v142
	ds_read_b128 v[2:5], v2
	s_waitcnt lgkmcnt(0)
	v_pk_fma_f32 v[2:3], v[14:15], v[12:13], v[2:3] op_sel_hi:[1,0,1]
	s_nop 0
	v_mul_f32_e32 v6, 0xbfb8aa3b, v2
	v_mul_f32_e32 v7, 0xbfb8aa3b, v3
	v_exp_f32_e32 v6, v6
	v_exp_f32_e32 v7, v7
	s_nop 0
	v_pk_add_f32 v[6:7], v[6:7], 1.0 op_sel_hi:[1,0]
	s_nop 0
	v_rcp_f32_e32 v9, v7
	s_nop 0
	v_mul_f32_e32 v14, v3, v9
	v_fma_f32 v15, -v7, v14, v3
	v_fma_f32 v8, v15, v9, v14
	v_div_fixup_f32 v3, v8, v7, v3
	v_rcp_f32_e32 v8, v6
	s_nop 0
	v_mul_f32_e32 v13, v2, v8
	v_fma_f32 v14, -v6, v13, v2
	v_fma_f32 v7, v14, v8, v13
	v_div_fixup_f32 v2, v7, v6, v2
	v_pk_fma_f32 v[4:5], v[16:17], v[12:13], v[4:5] op_sel_hi:[1,0,1]
	v_cvt_pk_bf16_f32 v2, v2, v3
	v_mul_f32_e32 v3, 0xbfb8aa3b, v4
	v_exp_f32_e32 v6, v3
	v_mul_f32_e32 v3, 0xbfb8aa3b, v5
	v_exp_f32_e32 v7, v3
	s_nop 0
	v_pk_add_f32 v[6:7], v[6:7], 1.0 op_sel_hi:[1,0]
	s_nop 0
	v_rcp_f32_e32 v8, v7
	s_nop 0
	v_mul_f32_e32 v13, v5, v8
	v_fma_f32 v14, -v7, v13, v5
	v_fma_f32 v3, v14, v8, v13
	v_div_fixup_f32 v3, v3, v7, v5
	v_rcp_f32_e32 v7, v6
	s_nop 0
	v_mul_f32_e32 v9, v4, v7
	v_fma_f32 v13, -v6, v9, v4
	v_fma_f32 v5, v13, v7, v9
	v_div_fixup_f32 v4, v5, v6, v4
	v_cvt_pk_bf16_f32 v3, v4, v3
	v_add_u32_e32 v4, 0x10a30, v142
	ds_read_b128 v[4:7], v4
	s_waitcnt lgkmcnt(0)
	v_pk_fma_f32 v[4:5], v[18:19], v[12:13], v[4:5] op_sel_hi:[1,0,1]
	s_nop 0
	v_mul_f32_e32 v8, 0xbfb8aa3b, v4
	v_mul_f32_e32 v9, 0xbfb8aa3b, v5
	v_exp_f32_e32 v8, v8
	v_exp_f32_e32 v9, v9
	s_nop 0
	v_pk_add_f32 v[8:9], v[8:9], 1.0 op_sel_hi:[1,0]
	s_nop 0
	v_rcp_f32_e32 v14, v9
	s_nop 0
	v_mul_f32_e32 v16, v5, v14
	v_fma_f32 v17, -v9, v16, v5
	v_fma_f32 v13, v17, v14, v16
	v_div_fixup_f32 v5, v13, v9, v5
	v_rcp_f32_e32 v13, v8
	s_nop 0
	v_mul_f32_e32 v15, v4, v13
	v_fma_f32 v16, -v8, v15, v4
	v_fma_f32 v9, v16, v13, v15
	v_div_fixup_f32 v4, v9, v8, v4
	v_pk_fma_f32 v[6:7], v[20:21], v[12:13], v[6:7] op_sel_hi:[1,0,1]
	v_cvt_pk_bf16_f32 v4, v4, v5
	v_mul_f32_e32 v5, 0xbfb8aa3b, v6
	v_exp_f32_e32 v8, v5
	v_mul_f32_e32 v5, 0xbfb8aa3b, v7
	v_exp_f32_e32 v9, v5
	s_nop 0
	v_pk_add_f32 v[8:9], v[8:9], 1.0 op_sel_hi:[1,0]
	s_nop 0
	v_rcp_f32_e32 v13, v9
	s_nop 0
	v_mul_f32_e32 v15, v7, v13
	v_fma_f32 v16, -v9, v15, v7
	v_fma_f32 v5, v16, v13, v15
	v_div_fixup_f32 v5, v5, v9, v7
	v_rcp_f32_e32 v9, v8
	s_nop 0
	v_mul_f32_e32 v14, v6, v9
	v_fma_f32 v15, -v8, v14, v6
	v_fma_f32 v7, v15, v9, v14
	v_div_fixup_f32 v6, v7, v8, v6
	v_cvt_pk_bf16_f32 v5, v6, v5
	v_add_u32_e32 v6, 0x10a40, v142
	global_store_dwordx4 v[10:11], v[2:5], off offset:16
	ds_read_b128 v[2:5], v197 offset:64
	ds_read_b128 v[6:9], v6
	s_waitcnt lgkmcnt(0)
	v_pk_fma_f32 v[2:3], v[2:3], v[12:13], v[6:7] op_sel_hi:[1,0,1]
	s_nop 0
	v_mul_f32_e32 v6, 0xbfb8aa3b, v2
	v_mul_f32_e32 v7, 0xbfb8aa3b, v3
	v_exp_f32_e32 v6, v6
	v_exp_f32_e32 v7, v7
	s_nop 0
	v_pk_add_f32 v[6:7], v[6:7], 1.0 op_sel_hi:[1,0]
	s_nop 0
	v_rcp_f32_e32 v14, v7
	s_nop 0
	v_mul_f32_e32 v16, v3, v14
	v_fma_f32 v17, -v7, v16, v3
	v_fma_f32 v13, v17, v14, v16
	v_div_fixup_f32 v3, v13, v7, v3
	v_rcp_f32_e32 v13, v6
	s_nop 0
	v_mul_f32_e32 v15, v2, v13
	v_fma_f32 v16, -v6, v15, v2
	v_fma_f32 v7, v16, v13, v15
	v_div_fixup_f32 v2, v7, v6, v2
	v_pk_fma_f32 v[4:5], v[4:5], v[12:13], v[8:9] op_sel_hi:[1,0,1]
	v_cvt_pk_bf16_f32 v2, v2, v3
	v_mul_f32_e32 v3, 0xbfb8aa3b, v4
	v_exp_f32_e32 v6, v3
	v_mul_f32_e32 v3, 0xbfb8aa3b, v5
	v_exp_f32_e32 v7, v3
	s_nop 0
	v_pk_add_f32 v[6:7], v[6:7], 1.0 op_sel_hi:[1,0]
	s_nop 0
	v_rcp_f32_e32 v8, v7
	s_nop 0
	v_mul_f32_e32 v13, v5, v8
	v_fma_f32 v14, -v7, v13, v5
	v_fma_f32 v3, v14, v8, v13
	v_div_fixup_f32 v3, v3, v7, v5
	v_rcp_f32_e32 v7, v6
	s_nop 0
	v_mul_f32_e32 v9, v4, v7
	v_fma_f32 v13, -v6, v9, v4
	v_fma_f32 v5, v13, v7, v9
	v_div_fixup_f32 v4, v5, v6, v4
	v_add_u32_e32 v8, 0x10a50, v142
	v_cvt_pk_bf16_f32 v3, v4, v3
	ds_read_b128 v[4:7], v197 offset:80
	ds_read_b128 v[14:17], v8
	s_waitcnt lgkmcnt(0)
	v_pk_fma_f32 v[4:5], v[4:5], v[12:13], v[14:15] op_sel_hi:[1,0,1]
	s_nop 0
	v_mul_f32_e32 v8, 0xbfb8aa3b, v4
	v_mul_f32_e32 v9, 0xbfb8aa3b, v5
	v_exp_f32_e32 v8, v8
	v_exp_f32_e32 v9, v9
	s_nop 0
	v_pk_add_f32 v[8:9], v[8:9], 1.0 op_sel_hi:[1,0]
	s_nop 0
	v_rcp_f32_e32 v14, v9
	s_nop 0
	v_mul_f32_e32 v18, v5, v14
	v_fma_f32 v19, -v9, v18, v5
	v_fma_f32 v13, v19, v14, v18
	v_div_fixup_f32 v5, v13, v9, v5
	v_rcp_f32_e32 v13, v8
	s_nop 0
	v_mul_f32_e32 v15, v4, v13
	v_fma_f32 v18, -v8, v15, v4
	v_fma_f32 v9, v18, v13, v15
	v_div_fixup_f32 v4, v9, v8, v4
	v_pk_fma_f32 v[6:7], v[6:7], v[12:13], v[16:17] op_sel_hi:[1,0,1]
	v_cvt_pk_bf16_f32 v4, v4, v5
	v_mul_f32_e32 v5, 0xbfb8aa3b, v6
	v_exp_f32_e32 v8, v5
	v_mul_f32_e32 v5, 0xbfb8aa3b, v7
	v_exp_f32_e32 v9, v5
	s_nop 0
	v_pk_add_f32 v[8:9], v[8:9], 1.0 op_sel_hi:[1,0]
	s_nop 0
	v_rcp_f32_e32 v13, v9
	s_nop 0
	v_mul_f32_e32 v15, v7, v13
	v_fma_f32 v16, -v9, v15, v7
	v_fma_f32 v5, v16, v13, v15
	v_div_fixup_f32 v5, v5, v9, v7
	v_rcp_f32_e32 v9, v8
	s_nop 0
	v_mul_f32_e32 v14, v6, v9
	v_fma_f32 v15, -v8, v14, v6
	v_fma_f32 v7, v15, v9, v14
	v_div_fixup_f32 v6, v7, v8, v6
	v_cvt_pk_bf16_f32 v5, v6, v5
	global_store_dwordx4 v[10:11], v[2:5], off offset:32
	v_add_u32_e32 v13, 0x10a60, v142
	ds_read_b128 v[2:5], v197 offset:96
	ds_read_b128 v[6:9], v197 offset:112
	ds_read_b128 v[14:17], v13
	s_waitcnt lgkmcnt(0)
	v_pk_fma_f32 v[2:3], v[2:3], v[12:13], v[14:15] op_sel_hi:[1,0,1]
	s_nop 0
	v_mul_f32_e32 v13, 0xbfb8aa3b, v2
	v_exp_f32_e32 v14, v13
	v_mul_f32_e32 v13, 0xbfb8aa3b, v3
	v_exp_f32_e32 v15, v13
	s_nop 0
	v_pk_add_f32 v[14:15], v[14:15], 1.0 op_sel_hi:[1,0]
	s_nop 0
	v_rcp_f32_e32 v18, v15
	s_nop 0
	v_mul_f32_e32 v20, v3, v18
	v_fma_f32 v21, -v15, v20, v3
	v_fma_f32 v13, v21, v18, v20
	v_div_fixup_f32 v3, v13, v15, v3
	v_rcp_f32_e32 v15, v14
	s_nop 0
	v_mul_f32_e32 v19, v2, v15
	v_fma_f32 v20, -v14, v19, v2
	v_fma_f32 v13, v20, v15, v19
	v_div_fixup_f32 v2, v13, v14, v2
	v_pk_fma_f32 v[4:5], v[4:5], v[12:13], v[16:17] op_sel_hi:[1,0,1]
	v_cvt_pk_bf16_f32 v2, v2, v3
	v_mul_f32_e32 v3, 0xbfb8aa3b, v4
	v_exp_f32_e32 v14, v3
	v_mul_f32_e32 v3, 0xbfb8aa3b, v5
	v_exp_f32_e32 v15, v3
	s_nop 0
	v_pk_add_f32 v[14:15], v[14:15], 1.0 op_sel_hi:[1,0]
	s_nop 0
	v_rcp_f32_e32 v13, v15
	s_nop 0
	v_mul_f32_e32 v17, v5, v13
	v_fma_f32 v18, -v15, v17, v5
	v_fma_f32 v3, v18, v13, v17
	v_div_fixup_f32 v3, v3, v15, v5
	v_rcp_f32_e32 v13, v14
	s_nop 0
	v_mul_f32_e32 v16, v4, v13
	v_fma_f32 v17, -v14, v16, v4
	v_fma_f32 v5, v17, v13, v16
	v_div_fixup_f32 v4, v5, v14, v4
	v_cvt_pk_bf16_f32 v3, v4, v3
	v_add_u32_e32 v4, 0x10a70, v142
	ds_read_b128 v[14:17], v4
	s_waitcnt lgkmcnt(0)
	v_pk_fma_f32 v[4:5], v[6:7], v[12:13], v[14:15] op_sel_hi:[1,0,1]
	s_nop 0
	v_mul_f32_e32 v6, 0xbfb8aa3b, v4
	v_mul_f32_e32 v7, 0xbfb8aa3b, v5
	v_exp_f32_e32 v6, v6
	v_exp_f32_e32 v7, v7
	s_nop 0
	v_pk_add_f32 v[6:7], v[6:7], 1.0 op_sel_hi:[1,0]
	s_nop 0
	v_rcp_f32_e32 v14, v7
	s_nop 0
	v_mul_f32_e32 v18, v5, v14
	v_fma_f32 v19, -v7, v18, v5
	v_fma_f32 v13, v19, v14, v18
	v_div_fixup_f32 v5, v13, v7, v5
	v_rcp_f32_e32 v13, v6
	s_nop 0
	v_mul_f32_e32 v15, v4, v13
	v_fma_f32 v18, -v6, v15, v4
	v_fma_f32 v7, v18, v13, v15
	v_div_fixup_f32 v4, v7, v6, v4
	v_pk_fma_f32 v[6:7], v[8:9], v[12:13], v[16:17] op_sel_hi:[1,0,1]
	v_cvt_pk_bf16_f32 v4, v4, v5
	v_mul_f32_e32 v5, 0xbfb8aa3b, v6
	v_exp_f32_e32 v8, v5
	v_mul_f32_e32 v5, 0xbfb8aa3b, v7
	v_exp_f32_e32 v9, v5
	s_nop 0
	v_pk_add_f32 v[8:9], v[8:9], 1.0 op_sel_hi:[1,0]
	s_nop 0
	v_rcp_f32_e32 v13, v9
	s_nop 0
	v_mul_f32_e32 v15, v7, v13
	v_fma_f32 v16, -v9, v15, v7
	v_fma_f32 v5, v16, v13, v15
	v_div_fixup_f32 v5, v5, v9, v7
	v_rcp_f32_e32 v9, v8
	s_nop 0
	v_mul_f32_e32 v14, v6, v9
	v_fma_f32 v15, -v8, v14, v6
	v_fma_f32 v7, v15, v9, v14
	v_div_fixup_f32 v6, v7, v8, v6
	v_cvt_pk_bf16_f32 v5, v6, v5
	global_store_dwordx4 v[10:11], v[2:5], off offset:48
	v_add_u32_e32 v13, 0x10a80, v142
	ds_read_b128 v[2:5], v197 offset:128
	ds_read_b128 v[6:9], v197 offset:144
	ds_read_b128 v[14:17], v13
	s_waitcnt lgkmcnt(0)
	v_pk_fma_f32 v[2:3], v[2:3], v[12:13], v[14:15] op_sel_hi:[1,0,1]
	s_nop 0
	v_mul_f32_e32 v13, 0xbfb8aa3b, v2
	v_exp_f32_e32 v14, v13
	v_mul_f32_e32 v13, 0xbfb8aa3b, v3
	v_exp_f32_e32 v15, v13
	s_nop 0
	v_pk_add_f32 v[14:15], v[14:15], 1.0 op_sel_hi:[1,0]
	s_nop 0
	v_rcp_f32_e32 v18, v15
	s_nop 0
	v_mul_f32_e32 v20, v3, v18
	v_fma_f32 v21, -v15, v20, v3
	v_fma_f32 v13, v21, v18, v20
	v_div_fixup_f32 v3, v13, v15, v3
	v_rcp_f32_e32 v15, v14
	s_nop 0
	v_mul_f32_e32 v19, v2, v15
	v_fma_f32 v20, -v14, v19, v2
	v_fma_f32 v13, v20, v15, v19
	v_div_fixup_f32 v2, v13, v14, v2
	v_pk_fma_f32 v[4:5], v[4:5], v[12:13], v[16:17] op_sel_hi:[1,0,1]
	v_cvt_pk_bf16_f32 v2, v2, v3
	v_mul_f32_e32 v3, 0xbfb8aa3b, v4
	v_exp_f32_e32 v14, v3
	v_mul_f32_e32 v3, 0xbfb8aa3b, v5
	v_exp_f32_e32 v15, v3
	s_nop 0
	v_pk_add_f32 v[14:15], v[14:15], 1.0 op_sel_hi:[1,0]
	s_nop 0
	v_rcp_f32_e32 v13, v15
	s_nop 0
	v_mul_f32_e32 v17, v5, v13
	v_fma_f32 v18, -v15, v17, v5
	v_fma_f32 v3, v18, v13, v17
	v_div_fixup_f32 v3, v3, v15, v5
	v_rcp_f32_e32 v13, v14
	s_nop 0
	v_mul_f32_e32 v16, v4, v13
	v_fma_f32 v17, -v14, v16, v4
	v_fma_f32 v5, v17, v13, v16
	v_div_fixup_f32 v4, v5, v14, v4
	v_cvt_pk_bf16_f32 v3, v4, v3
	v_add_u32_e32 v4, 0x10a90, v142
	ds_read_b128 v[14:17], v4
	s_waitcnt lgkmcnt(0)
	v_pk_fma_f32 v[4:5], v[6:7], v[12:13], v[14:15] op_sel_hi:[1,0,1]
	s_nop 0
	v_mul_f32_e32 v6, 0xbfb8aa3b, v4
	v_mul_f32_e32 v7, 0xbfb8aa3b, v5
	v_exp_f32_e32 v6, v6
	v_exp_f32_e32 v7, v7
	s_nop 0
	v_pk_add_f32 v[6:7], v[6:7], 1.0 op_sel_hi:[1,0]
	s_nop 0
	v_rcp_f32_e32 v14, v7
	s_nop 0
	v_mul_f32_e32 v18, v5, v14
	v_fma_f32 v19, -v7, v18, v5
	v_fma_f32 v13, v19, v14, v18
	v_div_fixup_f32 v5, v13, v7, v5
	v_rcp_f32_e32 v13, v6
	s_nop 0
	v_mul_f32_e32 v15, v4, v13
	v_fma_f32 v18, -v6, v15, v4
	v_fma_f32 v7, v18, v13, v15
	v_div_fixup_f32 v4, v7, v6, v4
	v_pk_fma_f32 v[6:7], v[8:9], v[12:13], v[16:17] op_sel_hi:[1,0,1]
	v_cvt_pk_bf16_f32 v4, v4, v5
	v_mul_f32_e32 v5, 0xbfb8aa3b, v6
	v_exp_f32_e32 v8, v5
	v_mul_f32_e32 v5, 0xbfb8aa3b, v7
	v_exp_f32_e32 v9, v5
	s_nop 0
	v_pk_add_f32 v[8:9], v[8:9], 1.0 op_sel_hi:[1,0]
	s_nop 0
	v_rcp_f32_e32 v13, v9
	s_nop 0
	v_mul_f32_e32 v15, v7, v13
	v_fma_f32 v16, -v9, v15, v7
	v_fma_f32 v5, v16, v13, v15
	v_div_fixup_f32 v5, v5, v9, v7
	v_rcp_f32_e32 v9, v8
	s_nop 0
	v_mul_f32_e32 v14, v6, v9
	v_fma_f32 v15, -v8, v14, v6
	v_fma_f32 v7, v15, v9, v14
	v_div_fixup_f32 v6, v7, v8, v6
	v_cvt_pk_bf16_f32 v5, v6, v5
	global_store_dwordx4 v[10:11], v[2:5], off offset:64
	v_add_u32_e32 v13, 0x10aa0, v142
	ds_read_b128 v[2:5], v197 offset:160
	ds_read_b128 v[6:9], v197 offset:176
	ds_read_b128 v[14:17], v13
	s_waitcnt lgkmcnt(0)
	v_pk_fma_f32 v[2:3], v[2:3], v[12:13], v[14:15] op_sel_hi:[1,0,1]
	s_nop 0
	v_mul_f32_e32 v13, 0xbfb8aa3b, v2
	v_exp_f32_e32 v14, v13
	v_mul_f32_e32 v13, 0xbfb8aa3b, v3
	v_exp_f32_e32 v15, v13
	s_nop 0
	v_pk_add_f32 v[14:15], v[14:15], 1.0 op_sel_hi:[1,0]
	s_nop 0
	v_rcp_f32_e32 v18, v15
	s_nop 0
	v_mul_f32_e32 v20, v3, v18
	v_fma_f32 v21, -v15, v20, v3
	v_fma_f32 v13, v21, v18, v20
	v_div_fixup_f32 v3, v13, v15, v3
	v_rcp_f32_e32 v15, v14
	s_nop 0
	v_mul_f32_e32 v19, v2, v15
	v_fma_f32 v20, -v14, v19, v2
	v_fma_f32 v13, v20, v15, v19
	v_div_fixup_f32 v2, v13, v14, v2
	v_pk_fma_f32 v[4:5], v[4:5], v[12:13], v[16:17] op_sel_hi:[1,0,1]
	v_cvt_pk_bf16_f32 v2, v2, v3
	v_mul_f32_e32 v3, 0xbfb8aa3b, v4
	v_exp_f32_e32 v14, v3
	v_mul_f32_e32 v3, 0xbfb8aa3b, v5
	v_exp_f32_e32 v15, v3
	s_nop 0
	v_pk_add_f32 v[14:15], v[14:15], 1.0 op_sel_hi:[1,0]
	s_nop 0
	v_rcp_f32_e32 v13, v15
	s_nop 0
	v_mul_f32_e32 v17, v5, v13
	v_fma_f32 v18, -v15, v17, v5
	v_fma_f32 v3, v18, v13, v17
	v_div_fixup_f32 v3, v3, v15, v5
	v_rcp_f32_e32 v13, v14
	s_nop 0
	v_mul_f32_e32 v16, v4, v13
	v_fma_f32 v17, -v14, v16, v4
	v_fma_f32 v5, v17, v13, v16
	v_div_fixup_f32 v4, v5, v14, v4
	v_cvt_pk_bf16_f32 v3, v4, v3
	v_add_u32_e32 v4, 0x10ab0, v142
	ds_read_b128 v[14:17], v4
	s_waitcnt lgkmcnt(0)
	v_pk_fma_f32 v[4:5], v[6:7], v[12:13], v[14:15] op_sel_hi:[1,0,1]
	s_nop 0
	v_mul_f32_e32 v6, 0xbfb8aa3b, v4
	v_mul_f32_e32 v7, 0xbfb8aa3b, v5
	v_exp_f32_e32 v6, v6
	v_exp_f32_e32 v7, v7
	s_nop 0
	v_pk_add_f32 v[6:7], v[6:7], 1.0 op_sel_hi:[1,0]
	s_nop 0
	v_rcp_f32_e32 v14, v7
	s_nop 0
	v_mul_f32_e32 v18, v5, v14
	v_fma_f32 v19, -v7, v18, v5
	v_fma_f32 v13, v19, v14, v18
	v_div_fixup_f32 v5, v13, v7, v5
	v_rcp_f32_e32 v13, v6
	s_nop 0
	v_mul_f32_e32 v15, v4, v13
	v_fma_f32 v18, -v6, v15, v4
	v_fma_f32 v7, v18, v13, v15
	v_div_fixup_f32 v4, v7, v6, v4
	v_pk_fma_f32 v[6:7], v[8:9], v[12:13], v[16:17] op_sel_hi:[1,0,1]
	v_cvt_pk_bf16_f32 v4, v4, v5
	v_mul_f32_e32 v5, 0xbfb8aa3b, v6
	v_exp_f32_e32 v8, v5
	v_mul_f32_e32 v5, 0xbfb8aa3b, v7
	v_exp_f32_e32 v9, v5
	s_nop 0
	v_pk_add_f32 v[8:9], v[8:9], 1.0 op_sel_hi:[1,0]
	s_nop 0
	v_rcp_f32_e32 v13, v9
	s_nop 0
	v_mul_f32_e32 v15, v7, v13
	v_fma_f32 v16, -v9, v15, v7
	v_fma_f32 v5, v16, v13, v15
	v_div_fixup_f32 v5, v5, v9, v7
	v_rcp_f32_e32 v9, v8
	s_nop 0
	v_mul_f32_e32 v14, v6, v9
	v_fma_f32 v15, -v8, v14, v6
	v_fma_f32 v7, v15, v9, v14
	v_div_fixup_f32 v6, v7, v8, v6
	v_cvt_pk_bf16_f32 v5, v6, v5
	global_store_dwordx4 v[10:11], v[2:5], off offset:80
	v_add_u32_e32 v13, 0x10ac0, v142
	ds_read_b128 v[2:5], v197 offset:192
	ds_read_b128 v[6:9], v197 offset:208
	ds_read_b128 v[14:17], v13
	s_waitcnt lgkmcnt(0)
	v_pk_fma_f32 v[2:3], v[2:3], v[12:13], v[14:15] op_sel_hi:[1,0,1]
	s_nop 0
	v_mul_f32_e32 v13, 0xbfb8aa3b, v2
	v_exp_f32_e32 v14, v13
	v_mul_f32_e32 v13, 0xbfb8aa3b, v3
	v_exp_f32_e32 v15, v13
	s_nop 0
	v_pk_add_f32 v[14:15], v[14:15], 1.0 op_sel_hi:[1,0]
	s_nop 0
	v_rcp_f32_e32 v18, v15
	s_nop 0
	v_mul_f32_e32 v20, v3, v18
	v_fma_f32 v21, -v15, v20, v3
	v_fma_f32 v13, v21, v18, v20
	v_div_fixup_f32 v3, v13, v15, v3
	v_rcp_f32_e32 v15, v14
	s_nop 0
	v_mul_f32_e32 v19, v2, v15
	v_fma_f32 v20, -v14, v19, v2
	v_fma_f32 v13, v20, v15, v19
	v_div_fixup_f32 v2, v13, v14, v2
	v_pk_fma_f32 v[4:5], v[4:5], v[12:13], v[16:17] op_sel_hi:[1,0,1]
	v_cvt_pk_bf16_f32 v2, v2, v3
	v_mul_f32_e32 v3, 0xbfb8aa3b, v4
	v_exp_f32_e32 v14, v3
	v_mul_f32_e32 v3, 0xbfb8aa3b, v5
	v_exp_f32_e32 v15, v3
	s_nop 0
	v_pk_add_f32 v[14:15], v[14:15], 1.0 op_sel_hi:[1,0]
	s_nop 0
	v_rcp_f32_e32 v13, v15
	s_nop 0
	v_mul_f32_e32 v17, v5, v13
	v_fma_f32 v18, -v15, v17, v5
	v_fma_f32 v3, v18, v13, v17
	v_div_fixup_f32 v3, v3, v15, v5
	v_rcp_f32_e32 v13, v14
	s_nop 0
	v_mul_f32_e32 v16, v4, v13
	v_fma_f32 v17, -v14, v16, v4
	v_fma_f32 v5, v17, v13, v16
	v_div_fixup_f32 v4, v5, v14, v4
	v_cvt_pk_bf16_f32 v3, v4, v3
	v_add_u32_e32 v4, 0x10ad0, v142
	ds_read_b128 v[14:17], v4
	s_waitcnt lgkmcnt(0)
	v_pk_fma_f32 v[4:5], v[6:7], v[12:13], v[14:15] op_sel_hi:[1,0,1]
	s_nop 0
	v_mul_f32_e32 v6, 0xbfb8aa3b, v4
	v_mul_f32_e32 v7, 0xbfb8aa3b, v5
	v_exp_f32_e32 v6, v6
	v_exp_f32_e32 v7, v7
	s_nop 0
	v_pk_add_f32 v[6:7], v[6:7], 1.0 op_sel_hi:[1,0]
	s_nop 0
	v_rcp_f32_e32 v14, v7
	s_nop 0
	v_mul_f32_e32 v18, v5, v14
	v_fma_f32 v19, -v7, v18, v5
	v_fma_f32 v13, v19, v14, v18
	v_div_fixup_f32 v5, v13, v7, v5
	v_rcp_f32_e32 v13, v6
	s_nop 0
	v_mul_f32_e32 v15, v4, v13
	v_fma_f32 v18, -v6, v15, v4
	v_fma_f32 v7, v18, v13, v15
	v_div_fixup_f32 v4, v7, v6, v4
	v_pk_fma_f32 v[6:7], v[8:9], v[12:13], v[16:17] op_sel_hi:[1,0,1]
	v_cvt_pk_bf16_f32 v4, v4, v5
	v_mul_f32_e32 v5, 0xbfb8aa3b, v6
	v_exp_f32_e32 v8, v5
	v_mul_f32_e32 v5, 0xbfb8aa3b, v7
	v_exp_f32_e32 v9, v5
	s_nop 0
	v_pk_add_f32 v[8:9], v[8:9], 1.0 op_sel_hi:[1,0]
	s_nop 0
	v_rcp_f32_e32 v13, v9
	s_nop 0
	v_mul_f32_e32 v15, v7, v13
	v_fma_f32 v16, -v9, v15, v7
	v_fma_f32 v5, v16, v13, v15
	v_div_fixup_f32 v5, v5, v9, v7
	v_rcp_f32_e32 v9, v8
	s_nop 0
	v_mul_f32_e32 v14, v6, v9
	v_fma_f32 v15, -v8, v14, v6
	v_fma_f32 v7, v15, v9, v14
	v_div_fixup_f32 v6, v7, v8, v6
	v_cvt_pk_bf16_f32 v5, v6, v5
	global_store_dwordx4 v[10:11], v[2:5], off offset:96
	v_add_u32_e32 v13, 0x10ae0, v142
	ds_read_b128 v[2:5], v197 offset:224
	ds_read_b128 v[6:9], v197 offset:240
	ds_read_b128 v[14:17], v13
	s_waitcnt lgkmcnt(0)
	v_pk_fma_f32 v[2:3], v[2:3], v[12:13], v[14:15] op_sel_hi:[1,0,1]
	s_nop 0
	v_mul_f32_e32 v13, 0xbfb8aa3b, v2
	v_exp_f32_e32 v14, v13
	v_mul_f32_e32 v13, 0xbfb8aa3b, v3
	v_exp_f32_e32 v15, v13
	s_nop 0
	v_pk_add_f32 v[14:15], v[14:15], 1.0 op_sel_hi:[1,0]
	s_nop 0
	v_rcp_f32_e32 v18, v15
	s_nop 0
	v_mul_f32_e32 v20, v3, v18
	v_fma_f32 v21, -v15, v20, v3
	v_fma_f32 v13, v21, v18, v20
	v_div_fixup_f32 v3, v13, v15, v3
	v_rcp_f32_e32 v15, v14
	s_nop 0
	v_mul_f32_e32 v19, v2, v15
	v_fma_f32 v20, -v14, v19, v2
	v_fma_f32 v13, v20, v15, v19
	v_div_fixup_f32 v2, v13, v14, v2
	v_pk_fma_f32 v[4:5], v[4:5], v[12:13], v[16:17] op_sel_hi:[1,0,1]
	v_cvt_pk_bf16_f32 v2, v2, v3
	v_mul_f32_e32 v3, 0xbfb8aa3b, v4
	v_exp_f32_e32 v14, v3
	v_mul_f32_e32 v3, 0xbfb8aa3b, v5
	v_exp_f32_e32 v15, v3
	s_nop 0
	v_pk_add_f32 v[14:15], v[14:15], 1.0 op_sel_hi:[1,0]
	s_nop 0
	v_rcp_f32_e32 v13, v15
	s_nop 0
	v_mul_f32_e32 v17, v5, v13
	v_fma_f32 v18, -v15, v17, v5
	v_fma_f32 v3, v18, v13, v17
	v_div_fixup_f32 v3, v3, v15, v5
	v_rcp_f32_e32 v13, v14
	s_nop 0
	v_mul_f32_e32 v16, v4, v13
	v_fma_f32 v17, -v14, v16, v4
	v_fma_f32 v5, v17, v13, v16
	v_div_fixup_f32 v4, v5, v14, v4
	v_cvt_pk_bf16_f32 v3, v4, v3
	v_add_u32_e32 v4, 0x10af0, v142
	ds_read_b128 v[14:17], v4
	s_waitcnt lgkmcnt(0)
	v_pk_fma_f32 v[4:5], v[6:7], v[12:13], v[14:15] op_sel_hi:[1,0,1]
	s_nop 0
	v_mul_f32_e32 v6, 0xbfb8aa3b, v4
	v_mul_f32_e32 v7, 0xbfb8aa3b, v5
	v_exp_f32_e32 v6, v6
	v_exp_f32_e32 v7, v7
	s_nop 0
	v_pk_add_f32 v[6:7], v[6:7], 1.0 op_sel_hi:[1,0]
	s_nop 0
	v_rcp_f32_e32 v14, v7
	s_nop 0
	v_mul_f32_e32 v18, v5, v14
	v_fma_f32 v19, -v7, v18, v5
	v_fma_f32 v13, v19, v14, v18
	v_div_fixup_f32 v5, v13, v7, v5
	v_rcp_f32_e32 v13, v6
	s_nop 0
	v_mul_f32_e32 v15, v4, v13
	v_fma_f32 v18, -v6, v15, v4
	v_fma_f32 v7, v18, v13, v15
	v_div_fixup_f32 v4, v7, v6, v4
	v_pk_fma_f32 v[6:7], v[8:9], v[12:13], v[16:17] op_sel_hi:[1,0,1]
	v_cvt_pk_bf16_f32 v4, v4, v5
	v_mul_f32_e32 v5, 0xbfb8aa3b, v6
	v_exp_f32_e32 v8, v5
	v_mul_f32_e32 v5, 0xbfb8aa3b, v7
	v_exp_f32_e32 v9, v5
	s_nop 0
	v_pk_add_f32 v[8:9], v[8:9], 1.0 op_sel_hi:[1,0]
	s_nop 0
	v_rcp_f32_e32 v12, v9
	s_nop 0
	v_mul_f32_e32 v14, v7, v12
	v_fma_f32 v15, -v9, v14, v7
	v_fma_f32 v5, v15, v12, v14
	v_div_fixup_f32 v5, v5, v9, v7
	v_div_scale_f32 v7, s[0:1], v8, v8, v6
	v_rcp_f32_e32 v9, v7
	s_mov_b64 s[0:1], 0
	v_fma_f32 v12, -v7, v9, 1.0
	v_fmac_f32_e32 v9, v12, v9
	v_div_scale_f32 v12, vcc, v6, v8, v6
	v_mul_f32_e32 v13, v12, v9
	v_fma_f32 v14, -v7, v13, v12
	v_fmac_f32_e32 v13, v14, v9
	v_fma_f32 v7, -v7, v13, v12
	v_div_fmas_f32 v7, v7, v9, v13
	v_div_fixup_f32 v6, v7, v8, v6
	v_cvt_pk_bf16_f32 v5, v6, v5
	global_store_dwordx4 v[10:11], v[2:5], off offset:112

.LBB0_211:
	ds_read_b128 v[214:217], v138
	ds_read_b128 v[218:221], v138 offset:32
	ds_read_b128 v[222:225], v138 offset:4608
	ds_read_b128 v[226:229], v138 offset:4640
	ds_read_b128 v[230:233], v139 offset:36864
	ds_read_b128 v[234:237], v139 offset:36896
	ds_read_b128 v[238:241], v139 offset:41472
	ds_read_b128 v[242:245], v139 offset:41504
	s_waitcnt vmcnt(15)
	ds_write_b128 v209, v[94:97] offset:18432
	buffer_load_dwordx4 v[94:97], v210, s[44:47], s0 offen
	s_waitcnt lgkmcnt(4)
	v_mfma_f32_32x32x16_bf16 v[50:65], v[214:217], v[230:233], v[50:65]
	s_add_u32 s24, s56, s0
	s_addc_u32 s20, s2, s1
	s_and_b32 s25, s20, 0xffff
	s_waitcnt lgkmcnt(2)
	v_mfma_f32_32x32x16_bf16 v[34:49], v[214:217], v[238:241], v[34:49]
	s_waitcnt vmcnt(15)
	ds_write_b128 v209, v[90:93] offset:55296
	buffer_load_dwordx4 v[90:93], v210, s[24:27], 0 offen
	v_mfma_f32_32x32x16_bf16 v[18:33], v[222:225], v[230:233], v[18:33]
	v_mfma_f32_32x32x16_bf16 v[2:17], v[222:225], v[238:241], v[2:17]
	s_add_i32 s20, s0, 0x11000
	ds_read_b128 v[214:217], v138 offset:64
	ds_read_b128 v[222:225], v138 offset:4672
	ds_read_b128 v[230:233], v139 offset:36928
	ds_read_b128 v[238:241], v139 offset:41536
	s_waitcnt vmcnt(15)
	ds_write_b128 v209, v[86:89] offset:23040
	buffer_load_dwordx4 v[86:89], v210, s[44:47], s20 offen
	v_mfma_f32_32x32x16_bf16 v[50:65], v[218:221], v[234:237], v[50:65]
	s_waitcnt lgkmcnt(7)
	v_mfma_f32_32x32x16_bf16 v[34:49], v[218:221], v[242:245], v[34:49]
	s_waitcnt vmcnt(15)
	ds_write_b128 v209, v[82:85] offset:59904
	buffer_load_dwordx4 v[82:85], v210, s[24:27], s33 offen
	v_mfma_f32_32x32x16_bf16 v[18:33], v[226:229], v[234:237], v[18:33]
	v_mfma_f32_32x32x16_bf16 v[2:17], v[226:229], v[242:245], v[2:17]
	s_add_i32 s20, s0, 0x22000
	ds_read_b128 v[218:221], v138 offset:96
	ds_read_b128 v[226:229], v138 offset:4704
	ds_read_b128 v[234:237], v139 offset:36960
	ds_read_b128 v[242:245], v139 offset:41568
	s_waitcnt vmcnt(15)
	ds_write_b128 v209, v[78:81] offset:27648
	buffer_load_dwordx4 v[78:81], v210, s[44:47], s20 offen
	s_waitcnt lgkmcnt(8)
	v_mfma_f32_32x32x16_bf16 v[50:65], v[214:217], v[230:233], v[50:65]
	s_waitcnt lgkmcnt(7)
	v_mfma_f32_32x32x16_bf16 v[34:49], v[214:217], v[238:241], v[34:49]
	s_waitcnt vmcnt(15)
	ds_write_b128 v209, v[74:77] offset:64512
	buffer_load_dwordx4 v[74:77], v210, s[24:27], s29 offen
	v_mfma_f32_32x32x16_bf16 v[18:33], v[222:225], v[230:233], v[18:33]
	v_mfma_f32_32x32x16_bf16 v[2:17], v[222:225], v[238:241], v[2:17]
	s_add_i32 s20, s0, 0x33000
	s_waitcnt vmcnt(15)
	ds_write_b128 v209, v[70:73] offset:32256
	buffer_load_dwordx4 v[70:73], v210, s[44:47], s20 offen
	s_waitcnt lgkmcnt(4)
	v_mfma_f32_32x32x16_bf16 v[50:65], v[218:221], v[234:237], v[50:65]
	s_waitcnt lgkmcnt(3)
	v_mfma_f32_32x32x16_bf16 v[34:49], v[218:221], v[242:245], v[34:49]
	s_waitcnt vmcnt(15)
	ds_write_b128 v212, v[66:69] offset:13824
	buffer_load_dwordx4 v[66:69], v210, s[24:27], s3 offen
	v_mfma_f32_32x32x16_bf16 v[18:33], v[226:229], v[234:237], v[18:33]
	v_mfma_f32_32x32x16_bf16 v[2:17], v[226:229], v[242:245], v[2:17]
	s_min_u32 s20, s54, 11
	s_lshl_b32 s20, s20, 7
	s_add_i32 s21, s20, 0x200
	s_waitcnt lgkmcnt(0)
	s_barrier
	s_cmp_eq_u32 s54, 12
	s_cbranch_scc1 .Llast_211
	ds_read_b128 v[214:217], v138 offset:18432
	ds_read_b128 v[218:221], v138 offset:18464
	ds_read_b128 v[222:225], v138 offset:23040
	ds_read_b128 v[226:229], v138 offset:23072
	ds_read_b128 v[230:233], v139 offset:55296
	ds_read_b128 v[234:237], v139 offset:55328
	ds_read_b128 v[238:241], v139 offset:59904
	ds_read_b128 v[242:245], v139 offset:59936
	s_waitcnt vmcnt(15)
	ds_write_b128 v209, v[102:105]
	buffer_load_dwordx4 v[102:105], v210, s[44:47], s21 offen
	s_waitcnt lgkmcnt(4)
	v_mfma_f32_32x32x16_bf16 v[50:65], v[214:217], v[230:233], v[50:65]
	s_add_u32 s24, s56, s21
	s_addc_u32 s21, s2, 0
	s_and_b32 s25, s21, 0xffff
	s_waitcnt lgkmcnt(2)
	v_mfma_f32_32x32x16_bf16 v[34:49], v[214:217], v[238:241], v[34:49]
	s_waitcnt vmcnt(15)
	ds_write_b128 v209, v[98:101] offset:36864
	buffer_load_dwordx4 v[98:101], v210, s[24:27], 0 offen
	v_mfma_f32_32x32x16_bf16 v[18:33], v[222:225], v[230:233], v[18:33]
	v_mfma_f32_32x32x16_bf16 v[2:17], v[222:225], v[238:241], v[2:17]
	s_add_i32 s21, s20, 0x11200
	ds_read_b128 v[214:217], v138 offset:18496
	ds_read_b128 v[222:225], v138 offset:23104
	ds_read_b128 v[230:233], v139 offset:55360
	ds_read_b128 v[238:241], v139 offset:59968
	s_waitcnt vmcnt(15)
	ds_write_b128 v209, v[106:109] offset:4608
	buffer_load_dwordx4 v[106:109], v210, s[44:47], s21 offen
	v_mfma_f32_32x32x16_bf16 v[50:65], v[218:221], v[234:237], v[50:65]
	s_waitcnt lgkmcnt(7)
	v_mfma_f32_32x32x16_bf16 v[34:49], v[218:221], v[242:245], v[34:49]
	s_waitcnt vmcnt(15)
	ds_write_b128 v209, v[110:113] offset:41472
	buffer_load_dwordx4 v[110:113], v210, s[24:27], s33 offen
	v_mfma_f32_32x32x16_bf16 v[18:33], v[226:229], v[234:237], v[18:33]
	v_mfma_f32_32x32x16_bf16 v[2:17], v[226:229], v[242:245], v[2:17]
	s_add_i32 s21, s20, 0x22200
	ds_read_b128 v[218:221], v138 offset:18528
	ds_read_b128 v[226:229], v138 offset:23136
	ds_read_b128 v[234:237], v139 offset:55392
	ds_read_b128 v[242:245], v139 offset:60000
	s_waitcnt vmcnt(15)
	ds_write_b128 v209, v[114:117] offset:9216
	buffer_load_dwordx4 v[114:117], v210, s[44:47], s21 offen
	s_waitcnt lgkmcnt(8)
	v_mfma_f32_32x32x16_bf16 v[50:65], v[214:217], v[230:233], v[50:65]
	s_waitcnt lgkmcnt(7)
	v_mfma_f32_32x32x16_bf16 v[34:49], v[214:217], v[238:241], v[34:49]
	s_waitcnt vmcnt(15)
	ds_write_b128 v209, v[118:121] offset:46080
	buffer_load_dwordx4 v[118:121], v210, s[24:27], s29 offen
	v_mfma_f32_32x32x16_bf16 v[18:33], v[222:225], v[230:233], v[18:33]
	v_mfma_f32_32x32x16_bf16 v[2:17], v[222:225], v[238:241], v[2:17]
	s_add_i32 s20, s20, 0x33200
	s_waitcnt vmcnt(15)
	ds_write_b128 v209, v[122:125] offset:13824
	buffer_load_dwordx4 v[122:125], v210, s[44:47], s20 offen
	s_waitcnt lgkmcnt(4)
	v_mfma_f32_32x32x16_bf16 v[50:65], v[218:221], v[234:237], v[50:65]
	s_waitcnt lgkmcnt(3)
	v_mfma_f32_32x32x16_bf16 v[34:49], v[218:221], v[242:245], v[34:49]
	s_waitcnt vmcnt(15)
	ds_write_b128 v209, v[126:129] offset:50688
	buffer_load_dwordx4 v[126:129], v210, s[24:27], s3 offen
	v_mfma_f32_32x32x16_bf16 v[18:33], v[226:229], v[234:237], v[18:33]
	v_mfma_f32_32x32x16_bf16 v[2:17], v[226:229], v[242:245], v[2:17]
	s_add_i32 s54, s54, 2
	s_add_u32 s0, s0, 0x100
	s_addc_u32 s1, s1, 0
	s_cmp_lt_u32 s54, 14
	s_waitcnt lgkmcnt(0)
	s_barrier
	s_cbranch_scc1 .LBB0_211
	s_branch .Ltail_211
.Llast_211:
	ds_read_b128 v[214:217], v138 offset:18432
	ds_read_b128 v[218:221], v138 offset:18464
	ds_read_b128 v[222:225], v138 offset:23040
	ds_read_b128 v[226:229], v138 offset:23072
	ds_read_b128 v[230:233], v139 offset:55296
	ds_read_b128 v[234:237], v139 offset:55328
	ds_read_b128 v[238:241], v139 offset:59904
	ds_read_b128 v[242:245], v139 offset:59936
	s_waitcnt vmcnt(15)
	ds_write_b128 v209, v[102:105]
	s_waitcnt lgkmcnt(4)
	v_mfma_f32_32x32x16_bf16 v[50:65], v[214:217], v[230:233], v[50:65]
	s_add_u32 s24, s56, s21
	s_addc_u32 s21, s2, 0
	s_and_b32 s25, s21, 0xffff
	s_waitcnt lgkmcnt(2)
	v_mfma_f32_32x32x16_bf16 v[34:49], v[214:217], v[238:241], v[34:49]
	s_waitcnt vmcnt(14)
	ds_write_b128 v209, v[98:101] offset:36864
	v_mfma_f32_32x32x16_bf16 v[18:33], v[222:225], v[230:233], v[18:33]
	v_mfma_f32_32x32x16_bf16 v[2:17], v[222:225], v[238:241], v[2:17]
	s_add_i32 s21, s20, 0x11200
	ds_read_b128 v[214:217], v138 offset:18496
	ds_read_b128 v[222:225], v138 offset:23104
	ds_read_b128 v[230:233], v139 offset:55360
	ds_read_b128 v[238:241], v139 offset:59968
	s_waitcnt vmcnt(13)
	ds_write_b128 v209, v[106:109] offset:4608
	v_mfma_f32_32x32x16_bf16 v[50:65], v[218:221], v[234:237], v[50:65]
	s_waitcnt lgkmcnt(7)
	v_mfma_f32_32x32x16_bf16 v[34:49], v[218:221], v[242:245], v[34:49]
	s_waitcnt vmcnt(12)
	ds_write_b128 v209, v[110:113] offset:41472
	v_mfma_f32_32x32x16_bf16 v[18:33], v[226:229], v[234:237], v[18:33]
	v_mfma_f32_32x32x16_bf16 v[2:17], v[226:229], v[242:245], v[2:17]
	s_add_i32 s21, s20, 0x22200
	ds_read_b128 v[218:221], v138 offset:18528
	ds_read_b128 v[226:229], v138 offset:23136
	ds_read_b128 v[234:237], v139 offset:55392
	ds_read_b128 v[242:245], v139 offset:60000
	s_waitcnt vmcnt(11)
	ds_write_b128 v209, v[114:117] offset:9216
	s_waitcnt lgkmcnt(8)
	v_mfma_f32_32x32x16_bf16 v[50:65], v[214:217], v[230:233], v[50:65]
	s_waitcnt lgkmcnt(7)
	v_mfma_f32_32x32x16_bf16 v[34:49], v[214:217], v[238:241], v[34:49]
	s_waitcnt vmcnt(10)
	ds_write_b128 v209, v[118:121] offset:46080
	v_mfma_f32_32x32x16_bf16 v[18:33], v[222:225], v[230:233], v[18:33]
	v_mfma_f32_32x32x16_bf16 v[2:17], v[222:225], v[238:241], v[2:17]
	s_add_i32 s20, s20, 0x33200
	s_waitcnt vmcnt(9)
	ds_write_b128 v209, v[122:125] offset:13824
	s_waitcnt lgkmcnt(4)
	v_mfma_f32_32x32x16_bf16 v[50:65], v[218:221], v[234:237], v[50:65]
	s_waitcnt lgkmcnt(3)
	v_mfma_f32_32x32x16_bf16 v[34:49], v[218:221], v[242:245], v[34:49]
	s_waitcnt vmcnt(8)
	ds_write_b128 v209, v[126:129] offset:50688
	v_mfma_f32_32x32x16_bf16 v[18:33], v[226:229], v[234:237], v[18:33]
	v_mfma_f32_32x32x16_bf16 v[2:17], v[226:229], v[242:245], v[2:17]
	s_add_i32 s54, s54, 2
	s_add_u32 s0, s0, 0x100
	s_addc_u32 s1, s1, 0
	s_cmp_lt_u32 s54, 14
	s_waitcnt lgkmcnt(0)
	s_barrier
	s_branch .Ltail_211
.Ltail_211:
	s_waitcnt vmcnt(6)
	ds_read_b128 v[98:101], v138
	ds_read_b128 v[102:105], v139 offset:36864
	s_waitcnt vmcnt(5)
	ds_read_b128 v[106:109], v138 offset:32
	s_waitcnt vmcnt(4)
	ds_read_b128 v[110:113], v139 offset:36896
	s_waitcnt vmcnt(3)
	ds_read_b128 v[114:117], v139 offset:41472
	s_waitcnt vmcnt(2)
	ds_read_b128 v[118:121], v138 offset:4608
	s_waitcnt vmcnt(1)
	ds_read_b128 v[122:125], v138 offset:4640
	s_waitcnt vmcnt(0)
	ds_read_b128 v[126:129], v139 offset:41504
	ds_write_b128 v209, v[94:97] offset:18432
	s_waitcnt lgkmcnt(7)
	v_mfma_f32_32x32x16_bf16 v[50:65], v[98:101], v[102:105], v[50:65]
	s_waitcnt lgkmcnt(4)
	v_mfma_f32_32x32x16_bf16 v[34:49], v[98:101], v[114:117], v[34:49]
	s_waitcnt lgkmcnt(3)
	v_mfma_f32_32x32x16_bf16 v[18:33], v[118:121], v[102:105], v[18:33]
	ds_write_b128 v209, v[90:93] offset:55296
	v_mfma_f32_32x32x16_bf16 v[2:17], v[118:121], v[114:117], v[2:17]
	ds_read_b128 v[90:93], v138 offset:64
	ds_read_b128 v[94:97], v138 offset:4672
	ds_read_b128 v[98:101], v139 offset:36928
	ds_read_b128 v[102:105], v139 offset:41536
	v_mfma_f32_32x32x16_bf16 v[50:65], v[106:109], v[110:113], v[50:65]
	ds_write_b128 v209, v[86:89] offset:23040
	s_waitcnt lgkmcnt(7)
	v_mfma_f32_32x32x16_bf16 v[34:49], v[106:109], v[126:129], v[34:49]
	v_mfma_f32_32x32x16_bf16 v[18:33], v[122:125], v[110:113], v[18:33]
	ds_write_b128 v209, v[82:85] offset:59904
	v_mfma_f32_32x32x16_bf16 v[2:17], v[122:125], v[126:129], v[2:17]
	ds_read_b128 v[82:85], v138 offset:96
	ds_read_b128 v[86:89], v138 offset:4704
	ds_read_b128 v[106:109], v139 offset:36960
	ds_read_b128 v[110:113], v139 offset:41568
	s_waitcnt lgkmcnt(7)
	v_mfma_f32_32x32x16_bf16 v[50:65], v[90:93], v[98:101], v[50:65]
	ds_write_b128 v209, v[78:81] offset:27648
	s_waitcnt lgkmcnt(7)
	v_mfma_f32_32x32x16_bf16 v[34:49], v[90:93], v[102:105], v[34:49]
	v_mfma_f32_32x32x16_bf16 v[18:33], v[94:97], v[98:101], v[18:33]
	ds_write_b128 v209, v[74:77] offset:64512
	v_mfma_f32_32x32x16_bf16 v[2:17], v[94:97], v[102:105], v[2:17]
	s_waitcnt lgkmcnt(3)
	v_mfma_f32_32x32x16_bf16 v[50:65], v[82:85], v[106:109], v[50:65]
	ds_write_b128 v209, v[70:73] offset:32256
	s_waitcnt lgkmcnt(3)
	v_mfma_f32_32x32x16_bf16 v[34:49], v[82:85], v[110:113], v[34:49]
	v_mfma_f32_32x32x16_bf16 v[18:33], v[86:89], v[106:109], v[18:33]
	ds_write_b128 v212, v[66:69] offset:13824
	v_mfma_f32_32x32x16_bf16 v[2:17], v[86:89], v[110:113], v[2:17]
	s_waitcnt lgkmcnt(0)
	s_barrier
	ds_read_b128 v[66:69], v138 offset:18432
	ds_read_b128 v[70:73], v139 offset:55296
	ds_read_b128 v[74:77], v138 offset:18464
	ds_read_b128 v[78:81], v139 offset:55328
	ds_read_b128 v[82:85], v139 offset:59904
	ds_read_b128 v[86:89], v138 offset:23040
	ds_read_b128 v[90:93], v138 offset:23072
	ds_read_b128 v[94:97], v139 offset:59936
	s_waitcnt lgkmcnt(6)
	v_mfma_f32_32x32x16_bf16 v[50:65], v[66:69], v[70:73], v[50:65]
	s_waitcnt lgkmcnt(3)
	v_mfma_f32_32x32x16_bf16 v[34:49], v[66:69], v[82:85], v[34:49]
	s_waitcnt lgkmcnt(2)
	v_mfma_f32_32x32x16_bf16 v[18:33], v[86:89], v[70:73], v[18:33]
	v_mfma_f32_32x32x16_bf16 v[2:17], v[86:89], v[82:85], v[2:17]
	ds_read_b128 v[66:69], v138 offset:18496
	ds_read_b128 v[70:73], v138 offset:23104
	ds_read_b128 v[82:85], v139 offset:55360
	ds_read_b128 v[86:89], v139 offset:59968
	v_mfma_f32_32x32x16_bf16 v[50:65], v[74:77], v[78:81], v[50:65]
	s_waitcnt lgkmcnt(4)
	v_mfma_f32_32x32x16_bf16 v[34:49], v[74:77], v[94:97], v[34:49]
	v_mfma_f32_32x32x16_bf16 v[18:33], v[90:93], v[78:81], v[18:33]
	v_mfma_f32_32x32x16_bf16 v[2:17], v[90:93], v[94:97], v[2:17]
	ds_read_b128 v[74:77], v138 offset:18528
	ds_read_b128 v[78:81], v138 offset:23136
	ds_read_b128 v[90:93], v139 offset:55392
	ds_read_b128 v[94:97], v139 offset:60000
	s_waitcnt lgkmcnt(5)
	v_mfma_f32_32x32x16_bf16 v[50:65], v[66:69], v[82:85], v[50:65]
	s_waitcnt lgkmcnt(4)
	v_mfma_f32_32x32x16_bf16 v[34:49], v[66:69], v[86:89], v[34:49]
	v_mfma_f32_32x32x16_bf16 v[18:33], v[70:73], v[82:85], v[18:33]
	v_mfma_f32_32x32x16_bf16 v[2:17], v[70:73], v[86:89], v[2:17]
	s_waitcnt lgkmcnt(1)
	v_mfma_f32_32x32x16_bf16 v[50:65], v[74:77], v[90:93], v[50:65]
	s_waitcnt lgkmcnt(0)
	v_mfma_f32_32x32x16_bf16 v[34:49], v[74:77], v[94:97], v[34:49]
	v_mfma_f32_32x32x16_bf16 v[18:33], v[78:81], v[90:93], v[18:33]
	v_mfma_f32_32x32x16_bf16 v[2:17], v[78:81], v[94:97], v[2:17]
	v_lshl_or_b32 v66, v208, 2, v211
	s_movk_i32 s0, 0x210
	v_and_or_b32 v67, v151, 64, v207
	v_mul_lo_u32 v66, v66, s0
	v_lshl_add_u32 v66, v67, 2, v66
	s_barrier
	s_nop 3
	ds_write2_b32 v66, v50, v34 offset1:32
	ds_write2_b32 v66, v51, v35 offset0:132 offset1:164
	v_add_u32_e32 v34, 0x400, v66
	ds_write2_b32 v34, v52, v36 offset0:8 offset1:40
	ds_write2_b32 v34, v53, v37 offset0:140 offset1:172
	v_add_u32_e32 v34, 0x1000, v66
	ds_write2_b32 v34, v54, v38 offset0:32 offset1:64
	ds_write2_b32 v34, v55, v39 offset0:164 offset1:196
	v_add_u32_e32 v34, 0x1400, v66
	ds_write2_b32 v34, v56, v40 offset0:40 offset1:72
	ds_write2_b32 v34, v57, v41 offset0:172 offset1:204
	v_add_u32_e32 v34, 0x2000, v66
	ds_write2_b32 v34, v58, v42 offset0:64 offset1:96
	ds_write2_b32 v34, v59, v43 offset0:196 offset1:228
	v_add_u32_e32 v34, 0x2400, v66
	ds_write2_b32 v34, v60, v44 offset0:72 offset1:104
	ds_write2_b32 v34, v61, v45 offset0:204 offset1:236
	v_add_u32_e32 v34, 0x3000, v66
	ds_write2_b32 v34, v62, v46 offset0:96 offset1:128
	v_add_u32_e32 v34, 0x3200, v66
	ds_write2_b32 v34, v63, v47 offset0:100 offset1:132
	v_add_u32_e32 v34, 0x3400, v66
	ds_write2_b32 v34, v64, v48 offset0:104 offset1:136
	v_add_u32_e32 v34, 0x3600, v66
	ds_write2_b32 v34, v65, v49 offset0:108 offset1:140
	v_add_u32_e32 v34, 0x4000, v66
	ds_write2_b32 v34, v18, v2 offset0:128 offset1:160
	v_add_u32_e32 v2, 0x4400, v66
	ds_write2_b32 v2, v19, v3 offset0:4 offset1:36
	ds_write2_b32 v2, v20, v4 offset0:136 offset1:168
	v_add_u32_e32 v2, 0x4800, v66
	ds_write2_b32 v2, v21, v5 offset0:12 offset1:44
	v_add_u32_e32 v2, 0x5000, v66
	ds_write2_b32 v2, v22, v6 offset0:160 offset1:192
	v_add_u32_e32 v2, 0x5400, v66
	ds_write2_b32 v2, v23, v7 offset0:36 offset1:68
	ds_write2_b32 v2, v24, v8 offset0:168 offset1:200
	v_add_u32_e32 v2, 0x5800, v66
	ds_write2_b32 v2, v25, v9 offset0:44 offset1:76
	v_add_u32_e32 v2, 0x6000, v66
	ds_write2_b32 v2, v26, v10 offset0:192 offset1:224
	v_add_u32_e32 v2, 0x6400, v66
	ds_write2_b32 v2, v27, v11 offset0:68 offset1:100
	ds_write2_b32 v2, v28, v12 offset0:200 offset1:232
	v_add_u32_e32 v2, 0x6800, v66
	ds_write2_b32 v2, v29, v13 offset0:76 offset1:108
	v_add_u32_e32 v2, 0x7200, v66
	ds_write2_b32 v2, v30, v14 offset0:96 offset1:128
	v_add_u32_e32 v2, 0x7400, v66
	ds_write2_b32 v2, v31, v15 offset0:100 offset1:132
	v_add_u32_e32 v2, 0x7600, v66
	ds_write2_b32 v2, v32, v16 offset0:104 offset1:136
	v_add_u32_e32 v2, 0x7800, v66
	s_and_b64 vcc, exec, s[40:41]
	ds_write2_b32 v2, v33, v17 offset0:108 offset1:140
	s_waitcnt lgkmcnt(0)
	s_barrier
	s_cbranch_vccnz .LBB0_215
	s_mov_b32 s54, 0x10800
	ds_write_b32 v133, v146
	s_waitcnt lgkmcnt(0)
	s_barrier
	s_branch .LBB0_216
